# nt (non-temporal) on P0 read-once f32 input loads (x, weights) on top of v28
# speedup vs baseline: 1.0832x; 1.0399x over previous
;     ...
;       for (int i = 0; i < 8; ++i) { const int kk = 8 * i + (lane >> 3); wv[i] = *(const f32x4*)(W + (size_t)(k0 + kk) * N + n0 + 4 * (lane & 7)); gv[i] = gain ? gain[k0 + kk] : 1.0f; }
; __device__ __forceinline__ void convert_item(const Args& a, int set, int it, LAS float* scr, int lane) {
;     ...
;         if (r < I_UP) { p0_transpose_item(a.in[I_F1W1], D, FF, a.in[I_F1N], (bf16_t*)(ws + WS_W13_1), 1, scr, r, lane); return; } r -= I_UP;
;         if (r < I_UP) { p0_transpose_item(a.in[I_F1W3], D, FF, a.in[I_F1N], (bf16_t*)(ws + WS_W13_1), 2, scr, r, lane); return; } r -= I_UP;
;         if (r < I_MKV) { p0_transpose_item(a.in[I_WMKV], D, 512, nullptr, (bf16_t*)(ws + WS_WMKV), 3, scr, r, lane); return; } r -= I_MKV;
;         if (r < I_DN) { p0_transpose_item(a.in[I_F1W2], FF, D, nullptr, (bf16_t*)(ws + WS_W2_1), 0, scr, r, lane); return; } r -= I_DN;
;         p0_transpose_item(a.in[I_WIN], D, QKVW, a.in[I_MIXN], (bf16_t*)(ws + WS_WIN), 3, scr, r, lane); return;
.LBB0_15:
	s_cmpk_gt_i32 s65, 0x57f
	s_mov_b64 s[8:9], -1
	s_cbranch_scc0 .LBB0_61
	s_cmpk_gt_u32 s65, 0xaff
	s_cbranch_scc0 .LBB0_42
	s_cmpk_gt_u32 s65, 0xbff
	s_cbranch_scc0 .LBB0_39
	s_cmpk_gt_u32 s65, 0x117f
	s_cbranch_scc0 .LBB0_36
	s_add_i32 s8, s65, 0xee80
	s_lshr_b32 s8, s8, 1
	s_and_b32 s27, s65, 0x7f
	s_and_b32 s26, s8, 0x7fc0
	v_or_b32_e32 v32, s26, v140
	s_lshl_b32 s22, s27, 7
	v_lshl_add_u64 v[30:31], v[36:37], 0, s[22:23]
	v_lshlrev_b32_e32 v34, 14, v32
	v_lshl_add_u64 v[2:3], v[30:31], 0, v[34:35]
	s_waitcnt lgkmcnt(3)
	global_load_dwordx4 v[2:5], v[2:3], off nt
	s_waitcnt lgkmcnt(2)
	v_cndmask_b32_e64 v6, 0, 1, s[36:37]
	v_mov_b32_e32 v124, 1.0
	v_cmp_ne_u32_e64 s[8:9], 1, v6
	s_andn2_b64 vcc, exec, s[36:37]
	v_lshlrev_b32_e32 v131, 2, v32
	v_mov_b32_e32 v126, 1.0
	s_cbranch_vccnz .LBB0_21
	global_load_dword v126, v131, s[24:25]
.LBB0_21:
	v_lshl_or_b32 v34, v32, 14, v147
	v_lshl_add_u64 v[6:7], v[30:31], 0, v[34:35]
	s_waitcnt lgkmcnt(0)
	global_load_dwordx4 v[6:9], v[6:7], off nt
	s_and_b64 vcc, exec, s[8:9]
	s_cbranch_vccnz .LBB0_23
	global_load_dword v124, v131, s[24:25] offset:32
.LBB0_23:
	v_lshl_or_b32 v34, v32, 14, v148
	v_lshl_add_u64 v[10:11], v[30:31], 0, v[34:35]
	global_load_dwordx4 v[10:13], v[10:11], off nt
	v_mov_b32_e32 v128, 1.0
	s_and_b64 vcc, exec, s[8:9]
	v_mov_b32_e32 v130, 1.0
	s_cbranch_vccnz .LBB0_25
	global_load_dword v130, v131, s[24:25] offset:64
.LBB0_25:
	v_lshl_or_b32 v34, v32, 14, v149
	v_lshl_add_u64 v[14:15], v[30:31], 0, v[34:35]
	global_load_dwordx4 v[14:17], v[14:15], off nt
	s_and_b64 vcc, exec, s[8:9]
	s_cbranch_vccnz .LBB0_27
	global_load_dword v128, v131, s[24:25] offset:96
.LBB0_27:
	v_lshl_or_b32 v34, v32, 14, v150
	v_lshl_add_u64 v[18:19], v[30:31], 0, v[34:35]
	global_load_dwordx4 v[18:21], v[18:19], off nt
	v_mov_b32_e32 v132, 1.0
	s_and_b64 vcc, exec, s[8:9]
	v_mov_b32_e32 v136, 1.0
	s_cbranch_vccnz .LBB0_29
	global_load_dword v136, v131, s[24:25] offset:128
.LBB0_29:
	v_lshl_or_b32 v34, v32, 14, v151
	v_lshl_add_u64 v[22:23], v[30:31], 0, v[34:35]
	global_load_dwordx4 v[22:25], v[22:23], off nt
	s_and_b64 vcc, exec, s[8:9]
	s_cbranch_vccnz .LBB0_31
	global_load_dword v132, v131, s[24:25] offset:160
.LBB0_31:
	v_lshl_or_b32 v34, v32, 14, v152
	v_lshl_add_u64 v[26:27], v[30:31], 0, v[34:35]
	global_load_dwordx4 v[26:29], v[26:27], off nt
	v_mov_b32_e32 v134, 1.0
	s_and_b64 vcc, exec, s[8:9]
	v_mov_b32_e32 v138, 1.0
	s_cbranch_vccnz .LBB0_33
	global_load_dword v138, v131, s[24:25] offset:192
.LBB0_33:
	v_lshl_or_b32 v34, v32, 14, v153
	v_lshl_add_u64 v[30:31], v[30:31], 0, v[34:35]
	global_load_dwordx4 v[30:33], v[30:31], off nt
	s_and_b64 vcc, exec, s[8:9]
	s_lshl_b32 s8, s27, 5
	s_cbranch_vccnz .LBB0_35
	global_load_dword v134, v131, s[24:25] offset:224

; #define LAS __attribute__((address_space(3)))
; __device__ __forceinline__ unsigned pk2(float lo, float hi) { f32x2 v = {lo, hi}; bf2_t b = __builtin_convertvector(v, bf2_t); return __builtin_bit_cast(unsigned, b); }
;     ...
;       for (int i = 0; i < 8; ++i) { const int kk = 8 * i + (lane >> 3); wv[i] = *(const f32x4*)(W + (size_t)(k0 + kk) * N + n0 + 4 * (lane & 7)); gv[i] = gain ? gain[k0 + kk] : 1.0f; }
; #pragma unroll
;       for (int i = 0; i < 8; ++i) { const int kk = 8 * i + (lane >> 3); LAS float* d = scr + kk * 33 + 4 * (lane & 7); d[0] = wv[i][0] * gv[i]; d[1] = wv[i][1] * gv[i]; d[2] = wv[i][2] * gv[i]; d[3] = wv[i][3] * gv[i]; } }
;     asm volatile("s_waitcnt lgkmcnt(0)" ::: "memory");
;     const int c = lane & 7; const int r0 = dst_row(dmode, n0);
; #pragma unroll
;     for (int j = 0; j < 4; ++j) { const int n = (lane >> 3) + 8 * j; const LAS float* s = scr + (8 * c) * 33 + n;
;         u32x4 o; o.x = pk2(s[0 * 33], s[1 * 33]); o.y = pk2(s[2 * 33], s[3 * 33]); o.z = pk2(s[4 * 33], s[5 * 33]); o.w = pk2(s[6 * 33], s[7 * 33]);
;         *(u32x4*)(WT + (size_t)(r0 + n) * pitch + k0 + 8 * c) = o; }
.LBB0_36:
	s_and_b64 vcc, exec, s[8:9]
	s_cbranch_vccz .LBB0_38
	s_and_b32 s9, s94, 0x1ffc0
	s_and_b32 s8, s78, 0x3e0
	s_waitcnt lgkmcnt(3)
	v_or_b32_e32 v4, s9, v140
	s_lshl_b32 s22, s8, 2
	v_lshl_add_u64 v[2:3], v[40:41], 0, s[22:23]
	v_lshlrev_b32_e32 v34, 12, v4
	v_lshl_add_u64 v[30:31], v[2:3], 0, v[34:35]
	s_waitcnt lgkmcnt(2)
	v_add_co_u32_e32 v6, vcc, 0x8000, v30
	v_add_u32_e32 v124, v105, v141
	s_nop 0
	v_addc_co_u32_e32 v7, vcc, 0, v31, vcc
	v_add_co_u32_e32 v10, vcc, 0x10000, v30
	global_load_dwordx4 v[2:5], v[30:31], off nt
	s_waitcnt lgkmcnt(0)
	global_load_dwordx4 v[6:9], v[6:7], off nt
	v_addc_co_u32_e32 v11, vcc, 0, v31, vcc
	v_add_co_u32_e32 v14, vcc, 0x18000, v30
	v_add_u32_e32 v126, 0x420, v124
	s_nop 0
	v_addc_co_u32_e32 v15, vcc, 0, v31, vcc
	v_add_co_u32_e32 v18, vcc, s71, v30
	global_load_dwordx4 v[10:13], v[10:11], off nt
	s_nop 0
	global_load_dwordx4 v[14:17], v[14:15], off nt
	v_addc_co_u32_e32 v19, vcc, 0, v31, vcc
	v_add_co_u32_e32 v22, vcc, 0x28000, v30
	v_add_u32_e32 v128, 0x428, v124
	s_nop 0
	v_addc_co_u32_e32 v23, vcc, 0, v31, vcc
	global_load_dwordx4 v[18:21], v[18:19], off nt
	s_nop 0
	global_load_dwordx4 v[22:25], v[22:23], off nt
	v_add_co_u32_e32 v26, vcc, 0x30000, v30
	v_add_u32_e32 v132, 0x840, v124
	s_nop 0
	v_addc_co_u32_e32 v27, vcc, 0, v31, vcc
	global_load_dwordx4 v[26:29], v[26:27], off nt
	v_add_co_u32_e32 v30, vcc, 0x38000, v30
	v_add_u32_e32 v134, 0x848, v124
	s_nop 0
	v_addc_co_u32_e32 v31, vcc, 0, v31, vcc
	global_load_dwordx4 v[30:33], v[30:31], off nt
	v_add_u32_e32 v136, 0xc60, v124
	v_add_u32_e32 v138, 0xc68, v124
	v_add_u32_e32 v156, 0x1080, v124
	v_add_u32_e32 v157, 0x1088, v124
	v_add_u32_e32 v158, 0x14a0, v124
	v_add_u32_e32 v159, 0x14a8, v124
	v_add_u32_e32 v160, 0x18c0, v124
	v_add_u32_e32 v161, 0x18c8, v124
	v_add_u32_e32 v162, 0x1ce0, v124
	v_add_u32_e32 v163, 0x1ce8, v124
	v_or_b32_e32 v34, s8, v140
	s_lshl_b32 s22, s9, 1
	v_mul_u32_u24_e32 v34, 0xb00, v34
	v_lshl_add_u64 v[130:131], v[42:43], 0, s[22:23]
	v_lshlrev_b32_e32 v34, 1, v34
	s_waitcnt vmcnt(7)
	ds_write2_b32 v124, v2, v3 offset1:1
	ds_write2_b32 v124, v4, v5 offset0:2 offset1:3
	s_waitcnt vmcnt(6)
	ds_write2_b32 v126, v6, v7 offset1:1
	ds_write2_b32 v128, v8, v9 offset1:1
	s_waitcnt vmcnt(5)
	ds_write2_b32 v132, v10, v11 offset1:1
	ds_write2_b32 v134, v12, v13 offset1:1
	s_waitcnt vmcnt(4)
	ds_write2_b32 v136, v14, v15 offset1:1
	ds_write2_b32 v138, v16, v17 offset1:1
	s_waitcnt vmcnt(3)
	ds_write2_b32 v156, v18, v19 offset1:1
	ds_write2_b32 v157, v20, v21 offset1:1
	s_waitcnt vmcnt(2)
	ds_write2_b32 v158, v22, v23 offset1:1
	ds_write2_b32 v159, v24, v25 offset1:1
	s_waitcnt vmcnt(1)
	ds_write2_b32 v160, v26, v27 offset1:1
	ds_write2_b32 v161, v28, v29 offset1:1
	s_waitcnt vmcnt(0)
	ds_write2_b32 v162, v30, v31 offset1:1
	ds_write2_b32 v163, v32, v33 offset1:1
	s_waitcnt lgkmcnt(0)
	ds_read2_b32 v[6:7], v155 offset0:33 offset1:41
	ds_read2_b32 v[8:9], v155 offset1:8
	ds_read2_b32 v[10:11], v155 offset0:66 offset1:74
	ds_read2_b32 v[12:13], v155 offset0:99 offset1:107
	ds_read2_b32 v[14:15], v155 offset0:132 offset1:140
	ds_read2_b32 v[16:17], v155 offset0:165 offset1:173
	ds_read2_b32 v[18:19], v155 offset0:198 offset1:206
	ds_read2_b32 v[20:21], v155 offset0:231 offset1:239
	v_lshl_add_u64 v[22:23], v[130:131], 0, v[34:35]
	s_waitcnt lgkmcnt(6)
	v_cvt_pk_bf16_f32 v2, v8, v6
	s_waitcnt lgkmcnt(4)
	v_cvt_pk_bf16_f32 v3, v10, v12
	s_waitcnt lgkmcnt(2)
	v_cvt_pk_bf16_f32 v4, v14, v16
	s_waitcnt lgkmcnt(0)
	v_cvt_pk_bf16_f32 v5, v18, v20
	global_store_dwordx4 v[22:23], v[2:5], off sc1
	v_cvt_pk_bf16_f32 v6, v9, v7
	v_cvt_pk_bf16_f32 v7, v11, v13
	v_or_b32_e32 v2, s8, v142
	v_mul_u32_u24_e32 v2, 0xb00, v2
	v_cvt_pk_bf16_f32 v8, v15, v17
	v_cvt_pk_bf16_f32 v9, v19, v21
	v_lshlrev_b32_e32 v34, 1, v2
	ds_read2_b32 v[10:11], v155 offset0:16 offset1:24
	ds_read2_b32 v[12:13], v155 offset0:49 offset1:57
	ds_read2_b32 v[14:15], v155 offset0:82 offset1:90
	ds_read2_b32 v[16:17], v155 offset0:115 offset1:123
	ds_read2_b32 v[18:19], v155 offset0:148 offset1:156
	ds_read2_b32 v[20:21], v155 offset0:181 offset1:189
	ds_read2_b32 v[22:23], v155 offset0:214 offset1:222
	ds_read2_b32 v[24:25], v155 offset0:247 offset1:255
	v_lshl_add_u64 v[2:3], v[130:131], 0, v[34:35]
	global_store_dwordx4 v[2:3], v[6:9], off sc1
	s_waitcnt lgkmcnt(6)
	v_cvt_pk_bf16_f32 v2, v10, v12
	s_waitcnt lgkmcnt(4)
	v_cvt_pk_bf16_f32 v3, v14, v16
	v_or_b32_e32 v6, s8, v143
	v_mul_u32_u24_e32 v6, 0xb00, v6
	v_lshlrev_b32_e32 v34, 1, v6
	s_waitcnt lgkmcnt(2)
	v_cvt_pk_bf16_f32 v4, v18, v20
	s_waitcnt lgkmcnt(0)
	v_cvt_pk_bf16_f32 v5, v22, v24
	v_lshl_add_u64 v[6:7], v[130:131], 0, v[34:35]
	global_store_dwordx4 v[6:7], v[2:5], off sc1
	v_or_b32_e32 v6, s8, v144
	v_mul_u32_u24_e32 v6, 0xb00, v6
	v_lshlrev_b32_e32 v34, 1, v6
	v_cvt_pk_bf16_f32 v2, v11, v13
	v_cvt_pk_bf16_f32 v3, v15, v17
	v_cvt_pk_bf16_f32 v4, v19, v21
	v_cvt_pk_bf16_f32 v5, v23, v25
	v_lshl_add_u64 v[6:7], v[130:131], 0, v[34:35]
	global_store_dwordx4 v[6:7], v[2:5], off sc1
	s_waitcnt lgkmcnt(0)

; #define LAS __attribute__((address_space(3)))
; __device__ __forceinline__ unsigned pk2(float lo, float hi) { f32x2 v = {lo, hi}; bf2_t b = __builtin_convertvector(v, bf2_t); return __builtin_bit_cast(unsigned, b); }
;     ...
;       for (int i = 0; i < 8; ++i) { const int kk = 8 * i + (lane >> 3); wv[i] = *(const f32x4*)(W + (size_t)(k0 + kk) * N + n0 + 4 * (lane & 7)); gv[i] = gain ? gain[k0 + kk] : 1.0f; }
; #pragma unroll
;       for (int i = 0; i < 8; ++i) { const int kk = 8 * i + (lane >> 3); LAS float* d = scr + kk * 33 + 4 * (lane & 7); d[0] = wv[i][0] * gv[i]; d[1] = wv[i][1] * gv[i]; d[2] = wv[i][2] * gv[i]; d[3] = wv[i][3] * gv[i]; } }
;     asm volatile("s_waitcnt lgkmcnt(0)" ::: "memory");
;     const int c = lane & 7; const int r0 = dst_row(dmode, n0);
; #pragma unroll
;     for (int j = 0; j < 4; ++j) { const int n = (lane >> 3) + 8 * j; const LAS float* s = scr + (8 * c) * 33 + n;
;         u32x4 o; o.x = pk2(s[0 * 33], s[1 * 33]); o.y = pk2(s[2 * 33], s[3 * 33]); o.z = pk2(s[4 * 33], s[5 * 33]); o.w = pk2(s[6 * 33], s[7 * 33]);
;         *(u32x4*)(WT + (size_t)(r0 + n) * pitch + k0 + 8 * c) = o; }
.LBB0_39:
	s_andn2_b64 vcc, exec, s[8:9]
	s_cbranch_vccnz .LBB0_41
	s_and_b32 s8, s96, 0x3c0
	s_and_b32 s9, s78, 0x1e0
	s_waitcnt lgkmcnt(3)
	v_or_b32_e32 v4, s8, v140
	s_lshl_b32 s22, s9, 2
	v_lshl_add_u64 v[2:3], v[44:45], 0, s[22:23]
	v_lshlrev_b32_e32 v34, 11, v4
	v_lshl_add_u64 v[30:31], v[2:3], 0, v[34:35]
	s_waitcnt lgkmcnt(2)
	v_add_co_u32_e32 v6, vcc, 0x4000, v30
	s_mov_b32 s9, 0x8000
	s_nop 0
	v_addc_co_u32_e32 v7, vcc, 0, v31, vcc
	v_add_co_u32_e32 v10, vcc, s9, v30
	s_mov_b32 s9, 0x10000
	s_nop 0
	v_addc_co_u32_e32 v11, vcc, 0, v31, vcc
	v_add_co_u32_e32 v14, vcc, 0xc000, v30
	global_load_dwordx4 v[2:5], v[30:31], off nt
	s_waitcnt lgkmcnt(0)
	global_load_dwordx4 v[6:9], v[6:7], off nt
	v_addc_co_u32_e32 v15, vcc, 0, v31, vcc
	v_add_co_u32_e32 v18, vcc, s9, v30
	global_load_dwordx4 v[10:13], v[10:11], off nt
	s_nop 0
	global_load_dwordx4 v[14:17], v[14:15], off nt
	v_addc_co_u32_e32 v19, vcc, 0, v31, vcc
	v_add_co_u32_e32 v22, vcc, 0x14000, v30
	s_mov_b32 s9, 0x18000
	s_nop 0
	v_addc_co_u32_e32 v23, vcc, 0, v31, vcc
	global_load_dwordx4 v[18:21], v[18:19], off nt
	s_nop 0
	global_load_dwordx4 v[22:25], v[22:23], off nt
	v_add_co_u32_e32 v26, vcc, s9, v30
	v_add_u32_e32 v34, v105, v141
	s_nop 0
	v_addc_co_u32_e32 v27, vcc, 0, v31, vcc
	global_load_dwordx4 v[26:29], v[26:27], off nt
	v_add_co_u32_e32 v30, vcc, 0x1c000, v30
	v_add_u32_e32 v124, 0x420, v34
	s_nop 0
	v_addc_co_u32_e32 v31, vcc, 0, v31, vcc
	global_load_dwordx4 v[30:33], v[30:31], off nt
	v_add_u32_e32 v126, 0x428, v34
	v_add_u32_e32 v128, 0x840, v34
	v_add_u32_e32 v130, 0x848, v34
	v_add_u32_e32 v131, 0xc60, v34
	v_add_u32_e32 v132, 0xc68, v34
	v_add_u32_e32 v134, 0x1080, v34
	v_add_u32_e32 v136, 0x1088, v34
	v_add_u32_e32 v138, 0x14a0, v34
	v_add_u32_e32 v156, 0x14a8, v34
	v_add_u32_e32 v157, 0x18c0, v34
	v_add_u32_e32 v158, 0x18c8, v34
	v_add_u32_e32 v159, 0x1ce0, v34
	v_add_u32_e32 v160, 0x1ce8, v34
	s_and_b32 s9, s78, 0x100
	s_and_b32 s22, s80, 0x80
	s_and_b32 s26, s63, 0x60
	s_or_b32 s9, s22, s9
	s_or_b32 s9, s9, s26
	s_lshl_b32 s22, s8, 1
	s_waitcnt vmcnt(7)
	ds_write2_b32 v34, v2, v3 offset1:1
	ds_write2_b32 v34, v4, v5 offset0:2 offset1:3
	s_waitcnt vmcnt(6)
	ds_write2_b32 v124, v6, v7 offset1:1
	ds_write2_b32 v126, v8, v9 offset1:1
	s_waitcnt vmcnt(5)
	ds_write2_b32 v128, v10, v11 offset1:1
	ds_write2_b32 v130, v12, v13 offset1:1
	s_waitcnt vmcnt(4)
	ds_write2_b32 v131, v14, v15 offset1:1
	ds_write2_b32 v132, v16, v17 offset1:1
	s_waitcnt vmcnt(3)
	ds_write2_b32 v134, v18, v19 offset1:1
	ds_write2_b32 v136, v20, v21 offset1:1
	s_waitcnt vmcnt(2)
	ds_write2_b32 v138, v22, v23 offset1:1
	ds_write2_b32 v156, v24, v25 offset1:1
	s_waitcnt vmcnt(1)
	ds_write2_b32 v157, v26, v27 offset1:1
	ds_write2_b32 v158, v28, v29 offset1:1
	s_waitcnt vmcnt(0)
	ds_write2_b32 v159, v30, v31 offset1:1
	ds_write2_b32 v160, v32, v33 offset1:1
	s_waitcnt lgkmcnt(0)
	ds_read2_b32 v[6:7], v155 offset0:33 offset1:41
	ds_read2_b32 v[8:9], v155 offset1:8
	ds_read2_b32 v[10:11], v155 offset0:66 offset1:74
	ds_read2_b32 v[12:13], v155 offset0:99 offset1:107
	ds_read2_b32 v[14:15], v155 offset0:132 offset1:140
	ds_read2_b32 v[16:17], v155 offset0:165 offset1:173
	ds_read2_b32 v[18:19], v155 offset0:198 offset1:206
	ds_read2_b32 v[20:21], v155 offset0:231 offset1:239
	s_waitcnt lgkmcnt(6)
	v_cvt_pk_bf16_f32 v2, v8, v6
	v_or_b32_e32 v6, s9, v140
	v_lshl_add_u64 v[22:23], v[46:47], 0, s[22:23]
	v_lshlrev_b32_e32 v34, 11, v6
	s_waitcnt lgkmcnt(4)
	v_cvt_pk_bf16_f32 v3, v10, v12
	s_waitcnt lgkmcnt(2)
	v_cvt_pk_bf16_f32 v4, v14, v16
	s_waitcnt lgkmcnt(0)
	v_cvt_pk_bf16_f32 v5, v18, v20
	v_lshl_add_u64 v[24:25], v[22:23], 0, v[34:35]
	global_store_dwordx4 v[24:25], v[2:5], off sc1
	v_or_b32_e32 v6, s9, v142
	v_lshlrev_b32_e32 v34, 11, v6
	v_cvt_pk_bf16_f32 v2, v9, v7
	v_cvt_pk_bf16_f32 v3, v11, v13
	v_cvt_pk_bf16_f32 v4, v15, v17
	v_cvt_pk_bf16_f32 v5, v19, v21
	ds_read2_b32 v[8:9], v155 offset0:49 offset1:57
	ds_read2_b32 v[10:11], v155 offset0:16 offset1:24
	ds_read2_b32 v[12:13], v155 offset0:82 offset1:90
	ds_read2_b32 v[14:15], v155 offset0:115 offset1:123
	ds_read2_b32 v[16:17], v155 offset0:148 offset1:156
	ds_read2_b32 v[18:19], v155 offset0:181 offset1:189
	ds_read2_b32 v[20:21], v155 offset0:214 offset1:222
	ds_read2_b32 v[24:25], v155 offset0:247 offset1:255
	v_lshl_add_u64 v[6:7], v[22:23], 0, v[34:35]
	global_store_dwordx4 v[6:7], v[2:5], off sc1
	v_or_b32_e32 v6, s9, v143
	v_lshlrev_b32_e32 v34, 11, v6
	s_waitcnt lgkmcnt(6)
	v_cvt_pk_bf16_f32 v2, v10, v8
	s_waitcnt lgkmcnt(4)
	v_cvt_pk_bf16_f32 v3, v12, v14
	s_waitcnt lgkmcnt(2)
	v_cvt_pk_bf16_f32 v4, v16, v18
	s_waitcnt lgkmcnt(0)
	v_cvt_pk_bf16_f32 v5, v20, v24
	v_lshl_add_u64 v[6:7], v[22:23], 0, v[34:35]
	global_store_dwordx4 v[6:7], v[2:5], off sc1
	v_or_b32_e32 v6, s9, v144
	v_lshlrev_b32_e32 v34, 11, v6
	v_cvt_pk_bf16_f32 v2, v11, v9
	v_cvt_pk_bf16_f32 v3, v13, v15
	v_cvt_pk_bf16_f32 v4, v17, v19
	v_cvt_pk_bf16_f32 v5, v21, v25
	v_lshl_add_u64 v[6:7], v[22:23], 0, v[34:35]
	global_store_dwordx4 v[6:7], v[2:5], off sc1
	s_waitcnt lgkmcnt(0)

;     ...
;       for (int i = 0; i < 8; ++i) { const int kk = 8 * i + (lane >> 3); wv[i] = *(const f32x4*)(W + (size_t)(k0 + kk) * N + n0 + 4 * (lane & 7)); gv[i] = gain ? gain[k0 + kk] : 1.0f; }
; __device__ __forceinline__ void convert_item(const Args& a, int set, int it, LAS float* scr, int lane) {
;     ...
;         if (r < I_UP) { p0_transpose_item(a.in[I_F1W3], D, FF, a.in[I_F1N], (bf16_t*)(ws + WS_W13_1), 2, scr, r, lane); return; } r -= I_UP;
.LBB0_42:
	s_andn2_b64 vcc, exec, s[8:9]
	s_cbranch_vccnz .LBB0_60
	s_add_i32 s8, s65, 0xfa80
	s_and_b32 s9, s8, 0xffff
	s_mul_i32 s9, s9, 0xba2f
	s_lshr_b32 s22, s9, 16
	s_lshr_b32 s9, s9, 22
	s_mulk_i32 s9, 0x58
	s_sub_i32 s8, s8, s9
	s_and_b32 s27, s8, 0xffff
	s_and_b32 s26, s22, 0xffc0
	s_lshl_b32 s22, s27, 7
	v_or_b32_e32 v32, s26, v140
	v_lshl_add_u64 v[30:31], v[48:49], 0, s[22:23]
	v_mad_u64_u32 v[2:3], s[8:9], v32, s87, v[30:31]
	s_waitcnt lgkmcnt(3)
	global_load_dwordx4 v[2:5], v[2:3], off nt
	s_waitcnt lgkmcnt(2)
	v_cndmask_b32_e64 v6, 0, 1, s[20:21]
	v_mov_b32_e32 v34, 1.0
	v_cmp_ne_u32_e64 s[8:9], 1, v6
	s_andn2_b64 vcc, exec, s[20:21]
	v_lshlrev_b32_e32 v131, 2, v32
	v_mov_b32_e32 v126, 1.0
	s_cbranch_vccnz .LBB0_45
	global_load_dword v126, v131, s[16:17]
.LBB0_45:
	v_or_b32_e32 v6, 8, v32
	v_mad_u64_u32 v[6:7], s[76:77], v6, s87, v[30:31]
	s_waitcnt lgkmcnt(0)
	global_load_dwordx4 v[6:9], v[6:7], off nt
	s_and_b64 vcc, exec, s[8:9]
	s_cbranch_vccnz .LBB0_47
	global_load_dword v34, v131, s[16:17] offset:32
.LBB0_47:
	v_or_b32_e32 v10, 16, v32
	v_mad_u64_u32 v[10:11], s[76:77], v10, s87, v[30:31]
	global_load_dwordx4 v[10:13], v[10:11], off nt
	v_mov_b32_e32 v124, 1.0
	s_and_b64 vcc, exec, s[8:9]
	v_mov_b32_e32 v130, 1.0
	s_cbranch_vccnz .LBB0_49
	global_load_dword v130, v131, s[16:17] offset:64
.LBB0_49:
	v_or_b32_e32 v14, 24, v32
	v_mad_u64_u32 v[14:15], s[76:77], v14, s87, v[30:31]
	global_load_dwordx4 v[14:17], v[14:15], off nt
	s_and_b64 vcc, exec, s[8:9]
	s_cbranch_vccnz .LBB0_51
	global_load_dword v124, v131, s[16:17] offset:96
.LBB0_51:
	v_or_b32_e32 v18, 32, v32
	v_mad_u64_u32 v[18:19], s[76:77], v18, s87, v[30:31]
	global_load_dwordx4 v[18:21], v[18:19], off nt
	v_mov_b32_e32 v128, 1.0
	s_and_b64 vcc, exec, s[8:9]
	v_mov_b32_e32 v134, 1.0
	s_cbranch_vccnz .LBB0_53
	global_load_dword v134, v131, s[16:17] offset:128
.LBB0_53:
	v_or_b32_e32 v22, 40, v32
	v_mad_u64_u32 v[22:23], s[76:77], v22, s87, v[30:31]
	global_load_dwordx4 v[22:25], v[22:23], off nt
	s_and_b64 vcc, exec, s[8:9]
	s_cbranch_vccnz .LBB0_55
	global_load_dword v128, v131, s[16:17] offset:160
.LBB0_55:
	v_or_b32_e32 v26, 48, v32
	v_mad_u64_u32 v[26:27], s[76:77], v26, s87, v[30:31]
	global_load_dwordx4 v[26:29], v[26:27], off nt
	v_mov_b32_e32 v132, 1.0
	s_and_b64 vcc, exec, s[8:9]
	v_mov_b32_e32 v136, 1.0
	s_cbranch_vccnz .LBB0_57
	global_load_dword v136, v131, s[16:17] offset:192
.LBB0_57:
	v_or_b32_e32 v32, 56, v32
	v_mad_u64_u32 v[30:31], s[76:77], v32, s87, v[30:31]
	global_load_dwordx4 v[30:33], v[30:31], off nt
	s_and_b64 vcc, exec, s[8:9]
	s_lshl_b32 s8, s27, 5
	s_cbranch_vccnz .LBB0_59
	global_load_dword v132, v131, s[16:17] offset:224

;     ...
;       for (int i = 0; i < 8; ++i) { const int kk = 8 * i + (lane >> 3); wv[i] = *(const f32x4*)(W + (size_t)(k0 + kk) * N + n0 + 4 * (lane & 7)); gv[i] = gain ? gain[k0 + kk] : 1.0f; }
; __device__ __forceinline__ void convert_item(const Args& a, int set, int it, LAS float* scr, int lane) {
;     ...
;         if (r < I_UP) { p0_transpose_item(a.in[I_F1W1], D, FF, a.in[I_F1N], (bf16_t*)(ws + WS_W13_1), 1, scr, r, lane); return; } r -= I_UP;
.LBB0_61:
	s_andn2_b64 vcc, exec, s[8:9]
	s_cbranch_vccnz .LBB0_14
	s_mul_hi_i32 s8, s65, 0x2e8ba2e9
	s_lshr_b32 s9, s8, 31
	s_ashr_i32 s22, s8, 4
	s_add_i32 s22, s22, s9
	s_mul_i32 s8, s22, 0xfffff500
	s_add_i32 s76, s78, s8
	s_lshl_b32 s26, s22, 6
	s_ashr_i32 s77, s76, 31
	v_or_b32_e32 v30, s26, v140
	v_lshl_add_u64 v[32:33], s[76:77], 2, v[52:53]
	v_mad_i64_i32 v[2:3], s[8:9], v30, s87, v[32:33]
	s_waitcnt lgkmcnt(3)
	global_load_dwordx4 v[2:5], v[2:3], off nt
	v_ashrrev_i32_e32 v31, 31, v30
	s_waitcnt lgkmcnt(2)
	v_cndmask_b32_e64 v6, 0, 1, s[20:21]
	v_mov_b32_e32 v34, 1.0
	v_cmp_ne_u32_e64 s[8:9], 1, v6
	s_andn2_b64 vcc, exec, s[20:21]
	v_lshl_add_u64 v[130:131], v[30:31], 2, s[16:17]
	v_mov_b32_e32 v126, 1.0
	s_cbranch_vccnz .LBB0_64
	global_load_dword v126, v[130:131], off
.LBB0_64:
	v_or_b32_e32 v6, 8, v30
	v_mad_i64_i32 v[6:7], vcc, v6, s87, v[32:33]
	s_waitcnt lgkmcnt(0)
	global_load_dwordx4 v[6:9], v[6:7], off nt
	s_and_b64 vcc, exec, s[8:9]
	s_cbranch_vccnz .LBB0_66
	global_load_dword v34, v[130:131], off offset:32
.LBB0_66:
	v_or_b32_e32 v10, 16, v30
	v_mad_i64_i32 v[10:11], vcc, v10, s87, v[32:33]
	global_load_dwordx4 v[10:13], v[10:11], off nt
	v_mov_b32_e32 v124, 1.0
	s_and_b64 vcc, exec, s[8:9]
	v_mov_b32_e32 v132, 1.0
	s_cbranch_vccnz .LBB0_68
	global_load_dword v132, v[130:131], off offset:64
.LBB0_68:
	v_or_b32_e32 v14, 24, v30
	v_mad_i64_i32 v[14:15], vcc, v14, s87, v[32:33]
	global_load_dwordx4 v[14:17], v[14:15], off nt
	s_and_b64 vcc, exec, s[8:9]
	s_cbranch_vccnz .LBB0_70
	global_load_dword v124, v[130:131], off offset:96
.LBB0_70:
	v_or_b32_e32 v18, 32, v30
	v_mad_i64_i32 v[18:19], vcc, v18, s87, v[32:33]
	global_load_dwordx4 v[18:21], v[18:19], off nt
	v_mov_b32_e32 v128, 1.0
	s_and_b64 vcc, exec, s[8:9]
	v_mov_b32_e32 v136, 1.0
	s_cbranch_vccnz .LBB0_72
	global_load_dword v136, v[130:131], off offset:128
.LBB0_72:
	v_or_b32_e32 v22, 40, v30
	v_mad_i64_i32 v[22:23], vcc, v22, s87, v[32:33]
	global_load_dwordx4 v[22:25], v[22:23], off nt
	s_and_b64 vcc, exec, s[8:9]
	s_cbranch_vccnz .LBB0_74
	global_load_dword v128, v[130:131], off offset:160
.LBB0_74:
	v_or_b32_e32 v26, 48, v30
	v_mad_i64_i32 v[26:27], vcc, v26, s87, v[32:33]
	global_load_dwordx4 v[26:29], v[26:27], off nt
	v_mov_b32_e32 v134, 1.0
	s_and_b64 vcc, exec, s[8:9]
	v_mov_b32_e32 v138, 1.0
	s_cbranch_vccnz .LBB0_76
	global_load_dword v138, v[130:131], off offset:192
.LBB0_76:
	v_or_b32_e32 v30, 56, v30
	v_mad_i64_i32 v[30:31], vcc, v30, s87, v[32:33]
	global_load_dwordx4 v[30:33], v[30:31], off nt
	s_and_b64 vcc, exec, s[8:9]
	s_cbranch_vccnz .LBB0_13
	global_load_dword v134, v[130:131], off offset:224
	s_branch .LBB0_13

; #define LAS __attribute__((address_space(3)))
; __device__ __forceinline__ unsigned pk2(float lo, float hi) { f32x2 v = {lo, hi}; bf2_t b = __builtin_convertvector(v, bf2_t); return __builtin_bit_cast(unsigned, b); }
;     ...
;       for (int i = 0; i < 8; ++i) { const int kk = 8 * i + (lane >> 3); wv[i] = *(const f32x4*)(W + (size_t)(k0 + kk) * N + n0 + 4 * (lane & 7)); gv[i] = gain ? gain[k0 + kk] : 1.0f; }
; #pragma unroll
;       for (int i = 0; i < 8; ++i) { const int kk = 8 * i + (lane >> 3); LAS float* d = scr + kk * 33 + 4 * (lane & 7); d[0] = wv[i][0] * gv[i]; d[1] = wv[i][1] * gv[i]; d[2] = wv[i][2] * gv[i]; d[3] = wv[i][3] * gv[i]; } }
;     asm volatile("s_waitcnt lgkmcnt(0)" ::: "memory");
;     const int c = lane & 7; const int r0 = dst_row(dmode, n0);
; #pragma unroll
;     for (int j = 0; j < 4; ++j) { const int n = (lane >> 3) + 8 * j; const LAS float* s = scr + (8 * c) * 33 + n;
;         u32x4 o; o.x = pk2(s[0 * 33], s[1 * 33]); o.y = pk2(s[2 * 33], s[3 * 33]); o.z = pk2(s[4 * 33], s[5 * 33]); o.w = pk2(s[6 * 33], s[7 * 33]);
;         *(u32x4*)(WT + (size_t)(r0 + n) * pitch + k0 + 8 * c) = o; }
; __device__ __forceinline__ void convert_item(const Args& a, int set, int it, LAS float* scr, int lane) {
;     ...
;     if (r < I_GT) { p0_transpose_item(a.in[I_WGATE], D, 3 * D, a.in[I_MIXN], (bf16_t*)(ws + WS_WG), 0, scr, r, lane); return; } r -= I_GT;
;     if (r < I_SB) { p0_transpose_item(a.in[I_WSB], 512, D, nullptr, (bf16_t*)(ws + WS_WSB), 0, scr, r, lane); return; } r -= I_SB;
;     if (r < I_DS) { p0_transpose_item(a.in[I_WDSA], 256, D, nullptr, (bf16_t*)(ws + WS_WDSA), 0, scr, r, lane, 512); return; } r -= I_DS;
;     if (r < I_DS) { p0_transpose_item(a.in[I_WMEM], 256, D, nullptr, (bf16_t*)(ws + WS_WMEM), 0, scr, r, lane, 512); return; } r -= I_DS;
;     if (r < I_OUT) { p0_transpose_item(a.in[I_WOUT], D, D, nullptr, (bf16_t*)(ws + WS_WOUT), 0, scr, r, lane); return; } r -= I_OUT;
;     if (r < I_UP) { p0_transpose_item(a.in[I_F2W1], D, FF, a.in[I_F2N], (bf16_t*)(ws + WS_W13_2), 1, scr, r, lane); return; } r -= I_UP;
;     if (r < I_UP) { p0_transpose_item(a.in[I_F2W3], D, FF, a.in[I_F2N], (bf16_t*)(ws + WS_W13_2), 2, scr, r, lane); return; } r -= I_UP;
;     p0_transpose_item(a.in[I_F2W2], FF, D, nullptr, (bf16_t*)(ws + WS_W2_2), 0, scr, r, lane);
.LBB0_82:
	s_cmpk_gt_i32 s93, 0x5ff
	s_mov_b64 s[8:9], -1
	s_cbranch_scc0 .LBB0_140
	s_cmpk_gt_u32 s93, 0x6ff
	s_cbranch_scc0 .LBB0_137
	s_cmpk_gt_u32 s93, 0x77f
	s_cbranch_scc0 .LBB0_134
	s_cmpk_gt_u32 s93, 0x7ff
	s_cbranch_scc0 .LBB0_131
	s_cmpk_gt_u32 s93, 0x9ff
	s_cbranch_scc0 .LBB0_128
	s_cmpk_gt_u32 s93, 0xf7f
	s_cbranch_scc0 .LBB0_109
	s_cmpk_gt_u32 s93, 0x14ff
	s_cbranch_scc0 .LBB0_90
	s_add_i32 s8, s79, 0x1d600
	s_and_b32 s8, s8, 0x1ffc0
	s_and_b32 s9, s13, 0x3e0
	s_waitcnt lgkmcnt(3)
	v_or_b32_e32 v4, s8, v140
	s_lshl_b32 s22, s9, 2
	v_lshl_add_u64 v[2:3], v[54:55], 0, s[22:23]
	v_lshlrev_b32_e32 v34, 12, v4
	v_lshl_add_u64 v[30:31], v[2:3], 0, v[34:35]
	s_waitcnt lgkmcnt(2)
	v_add_co_u32_e32 v6, vcc, 0x8000, v30
	v_add_u32_e32 v124, v105, v141
	s_nop 0
	v_addc_co_u32_e32 v7, vcc, 0, v31, vcc
	v_add_co_u32_e32 v10, vcc, 0x10000, v30
	global_load_dwordx4 v[2:5], v[30:31], off nt
	s_waitcnt lgkmcnt(0)
	global_load_dwordx4 v[6:9], v[6:7], off nt
	v_addc_co_u32_e32 v11, vcc, 0, v31, vcc
	v_add_co_u32_e32 v14, vcc, 0x18000, v30
	v_add_u32_e32 v126, 0x420, v124
	s_nop 0
	v_addc_co_u32_e32 v15, vcc, 0, v31, vcc
	v_add_co_u32_e32 v18, vcc, s71, v30
	global_load_dwordx4 v[10:13], v[10:11], off nt
	s_nop 0
	global_load_dwordx4 v[14:17], v[14:15], off nt
	v_addc_co_u32_e32 v19, vcc, 0, v31, vcc
	v_add_co_u32_e32 v22, vcc, 0x28000, v30
	v_add_u32_e32 v128, 0x428, v124
	s_nop 0
	v_addc_co_u32_e32 v23, vcc, 0, v31, vcc
	global_load_dwordx4 v[18:21], v[18:19], off nt
	s_nop 0
	global_load_dwordx4 v[22:25], v[22:23], off nt
	v_add_co_u32_e32 v26, vcc, 0x30000, v30
	v_add_u32_e32 v132, 0x840, v124
	s_nop 0
	v_addc_co_u32_e32 v27, vcc, 0, v31, vcc
	global_load_dwordx4 v[26:29], v[26:27], off nt
	v_add_co_u32_e32 v30, vcc, 0x38000, v30
	v_add_u32_e32 v134, 0x848, v124
	s_nop 0
	v_addc_co_u32_e32 v31, vcc, 0, v31, vcc
	global_load_dwordx4 v[30:33], v[30:31], off nt
	v_add_u32_e32 v136, 0xc60, v124
	v_add_u32_e32 v138, 0xc68, v124
	v_add_u32_e32 v156, 0x1080, v124
	v_add_u32_e32 v157, 0x1088, v124
	v_add_u32_e32 v158, 0x14a0, v124
	v_add_u32_e32 v159, 0x14a8, v124
	v_add_u32_e32 v160, 0x18c0, v124
	v_add_u32_e32 v161, 0x18c8, v124
	v_add_u32_e32 v162, 0x1ce0, v124
	v_add_u32_e32 v163, 0x1ce8, v124
	v_or_b32_e32 v34, s9, v140
	s_lshl_b32 s22, s8, 1
	v_mul_u32_u24_e32 v34, 0xb00, v34
	v_lshl_add_u64 v[130:131], v[56:57], 0, s[22:23]
	v_lshlrev_b32_e32 v34, 1, v34
	s_waitcnt vmcnt(7)
	ds_write2_b32 v124, v2, v3 offset1:1
	ds_write2_b32 v124, v4, v5 offset0:2 offset1:3
	s_waitcnt vmcnt(6)
	ds_write2_b32 v126, v6, v7 offset1:1
	ds_write2_b32 v128, v8, v9 offset1:1
	s_waitcnt vmcnt(5)
	ds_write2_b32 v132, v10, v11 offset1:1
	ds_write2_b32 v134, v12, v13 offset1:1
	s_waitcnt vmcnt(4)
	ds_write2_b32 v136, v14, v15 offset1:1
	ds_write2_b32 v138, v16, v17 offset1:1
	s_waitcnt vmcnt(3)
	ds_write2_b32 v156, v18, v19 offset1:1
	ds_write2_b32 v157, v20, v21 offset1:1
	s_waitcnt vmcnt(2)
	ds_write2_b32 v158, v22, v23 offset1:1
	ds_write2_b32 v159, v24, v25 offset1:1
	s_waitcnt vmcnt(1)
	ds_write2_b32 v160, v26, v27 offset1:1
	ds_write2_b32 v161, v28, v29 offset1:1
	s_waitcnt vmcnt(0)
	ds_write2_b32 v162, v30, v31 offset1:1
	ds_write2_b32 v163, v32, v33 offset1:1
	s_waitcnt lgkmcnt(0)
	ds_read2_b32 v[6:7], v155 offset0:33 offset1:41
	ds_read2_b32 v[8:9], v155 offset1:8
	ds_read2_b32 v[10:11], v155 offset0:66 offset1:74
	ds_read2_b32 v[12:13], v155 offset0:99 offset1:107
	ds_read2_b32 v[14:15], v155 offset0:132 offset1:140
	ds_read2_b32 v[16:17], v155 offset0:165 offset1:173
	ds_read2_b32 v[18:19], v155 offset0:198 offset1:206
	ds_read2_b32 v[20:21], v155 offset0:231 offset1:239
	v_lshl_add_u64 v[22:23], v[130:131], 0, v[34:35]
	s_waitcnt lgkmcnt(6)
	v_cvt_pk_bf16_f32 v2, v8, v6
	s_waitcnt lgkmcnt(4)
	v_cvt_pk_bf16_f32 v3, v10, v12
	s_waitcnt lgkmcnt(2)
	v_cvt_pk_bf16_f32 v4, v14, v16
	s_waitcnt lgkmcnt(0)
	v_cvt_pk_bf16_f32 v5, v18, v20
	v_or_b32_e32 v6, s9, v142
	global_store_dwordx4 v[22:23], v[2:5], off sc1
	v_mul_u32_u24_e32 v6, 0xb00, v6
	v_lshlrev_b32_e32 v34, 1, v6
	v_cvt_pk_bf16_f32 v2, v9, v7
	v_cvt_pk_bf16_f32 v3, v11, v13
	v_cvt_pk_bf16_f32 v4, v15, v17
	v_cvt_pk_bf16_f32 v5, v19, v21
	ds_read2_b32 v[8:9], v155 offset0:16 offset1:24
	ds_read2_b32 v[10:11], v155 offset0:49 offset1:57
	ds_read2_b32 v[12:13], v155 offset0:82 offset1:90
	ds_read2_b32 v[14:15], v155 offset0:115 offset1:123
	ds_read2_b32 v[16:17], v155 offset0:148 offset1:156
	ds_read2_b32 v[18:19], v155 offset0:181 offset1:189
	ds_read2_b32 v[20:21], v155 offset0:214 offset1:222
	ds_read2_b32 v[22:23], v155 offset0:247 offset1:255
	v_lshl_add_u64 v[6:7], v[130:131], 0, v[34:35]
	global_store_dwordx4 v[6:7], v[2:5], off sc1
	v_or_b32_e32 v6, s9, v143
	v_mul_u32_u24_e32 v6, 0xb00, v6
	v_lshlrev_b32_e32 v34, 1, v6
	s_waitcnt lgkmcnt(6)
	v_cvt_pk_bf16_f32 v2, v8, v10
	s_waitcnt lgkmcnt(4)
	v_cvt_pk_bf16_f32 v3, v12, v14
	s_waitcnt lgkmcnt(2)
	v_cvt_pk_bf16_f32 v4, v16, v18
	s_waitcnt lgkmcnt(0)
	v_cvt_pk_bf16_f32 v5, v20, v22
	v_lshl_add_u64 v[6:7], v[130:131], 0, v[34:35]
	global_store_dwordx4 v[6:7], v[2:5], off sc1
	v_or_b32_e32 v6, s9, v144
	v_mul_u32_u24_e32 v6, 0xb00, v6
	v_lshlrev_b32_e32 v34, 1, v6
	v_cvt_pk_bf16_f32 v2, v9, v11
	v_cvt_pk_bf16_f32 v3, v13, v15
	v_cvt_pk_bf16_f32 v4, v17, v19
	v_cvt_pk_bf16_f32 v5, v21, v23
	v_lshl_add_u64 v[6:7], v[130:131], 0, v[34:35]
	global_store_dwordx4 v[6:7], v[2:5], off sc1
	s_waitcnt lgkmcnt(0)
	s_mov_b64 s[8:9], 0
;     ...
;       for (int i = 0; i < 8; ++i) { const int kk = 8 * i + (lane >> 3); wv[i] = *(const f32x4*)(W + (size_t)(k0 + kk) * N + n0 + 4 * (lane & 7)); gv[i] = gain ? gain[k0 + kk] : 1.0f; }
; __device__ __forceinline__ void convert_item(const Args& a, int set, int it, LAS float* scr, int lane) {
;     ...
;     if (r < I_UP) { p0_transpose_item(a.in[I_F2W3], D, FF, a.in[I_F2N], (bf16_t*)(ws + WS_W13_2), 2, scr, r, lane); return; } r -= I_UP;
.LBB0_90:
	s_andn2_b64 vcc, exec, s[8:9]
	s_cbranch_vccnz .LBB0_108
	s_add_i32 s8, s93, 0xf080
	s_and_b32 s9, s8, 0xffff
	s_mul_i32 s9, s9, 0xba2f
	s_lshr_b32 s22, s9, 16
	s_lshr_b32 s9, s9, 22
	s_mulk_i32 s9, 0x58
	s_sub_i32 s8, s8, s9
	s_and_b32 s27, s8, 0xffff
	s_and_b32 s26, s22, 0xffc0
	s_lshl_b32 s22, s27, 7
	v_or_b32_e32 v32, s26, v140
	v_lshl_add_u64 v[30:31], v[58:59], 0, s[22:23]
	v_mad_u64_u32 v[2:3], s[8:9], v32, s87, v[30:31]
	s_waitcnt lgkmcnt(3)
	global_load_dwordx4 v[2:5], v[2:3], off nt
	s_waitcnt lgkmcnt(2)
	v_cndmask_b32_e64 v6, 0, 1, s[18:19]
	v_mov_b32_e32 v34, 1.0
	v_cmp_ne_u32_e64 s[8:9], 1, v6
	s_andn2_b64 vcc, exec, s[18:19]
	v_lshlrev_b32_e32 v131, 2, v32
	v_mov_b32_e32 v126, 1.0
	s_cbranch_vccnz .LBB0_93
	global_load_dword v126, v131, s[54:55]
.LBB0_93:
	v_or_b32_e32 v6, 8, v32
	v_mad_u64_u32 v[6:7], s[62:63], v6, s87, v[30:31]
	s_waitcnt lgkmcnt(0)
	global_load_dwordx4 v[6:9], v[6:7], off nt
	s_and_b64 vcc, exec, s[8:9]
	s_cbranch_vccnz .LBB0_95
	global_load_dword v34, v131, s[54:55] offset:32
.LBB0_95:
	v_or_b32_e32 v10, 16, v32
	v_mad_u64_u32 v[10:11], s[62:63], v10, s87, v[30:31]
	global_load_dwordx4 v[10:13], v[10:11], off nt
	v_mov_b32_e32 v124, 1.0
	s_and_b64 vcc, exec, s[8:9]
	v_mov_b32_e32 v130, 1.0
	s_cbranch_vccnz .LBB0_97
	global_load_dword v130, v131, s[54:55] offset:64
.LBB0_97:
	v_or_b32_e32 v14, 24, v32
	v_mad_u64_u32 v[14:15], s[62:63], v14, s87, v[30:31]
	global_load_dwordx4 v[14:17], v[14:15], off nt
	s_and_b64 vcc, exec, s[8:9]
	s_cbranch_vccnz .LBB0_99
	global_load_dword v124, v131, s[54:55] offset:96
.LBB0_99:
	v_or_b32_e32 v18, 32, v32
	v_mad_u64_u32 v[18:19], s[62:63], v18, s87, v[30:31]
	global_load_dwordx4 v[18:21], v[18:19], off nt
	v_mov_b32_e32 v128, 1.0
	s_and_b64 vcc, exec, s[8:9]
	v_mov_b32_e32 v134, 1.0
	s_cbranch_vccnz .LBB0_101
	global_load_dword v134, v131, s[54:55] offset:128
.LBB0_101:
	v_or_b32_e32 v22, 40, v32
	v_mad_u64_u32 v[22:23], s[62:63], v22, s87, v[30:31]
	global_load_dwordx4 v[22:25], v[22:23], off nt
	s_and_b64 vcc, exec, s[8:9]
	s_cbranch_vccnz .LBB0_103
	global_load_dword v128, v131, s[54:55] offset:160
.LBB0_103:
	v_or_b32_e32 v26, 48, v32
	v_mad_u64_u32 v[26:27], s[62:63], v26, s87, v[30:31]
	global_load_dwordx4 v[26:29], v[26:27], off nt
	v_mov_b32_e32 v132, 1.0
	s_and_b64 vcc, exec, s[8:9]
	v_mov_b32_e32 v136, 1.0
	s_cbranch_vccnz .LBB0_105
	global_load_dword v136, v131, s[54:55] offset:192
.LBB0_105:
	v_or_b32_e32 v32, 56, v32
	v_mad_u64_u32 v[30:31], s[62:63], v32, s87, v[30:31]
	global_load_dwordx4 v[30:33], v[30:31], off nt
	s_and_b64 vcc, exec, s[8:9]
	s_lshl_b32 s8, s27, 5
	s_cbranch_vccnz .LBB0_107
	global_load_dword v132, v131, s[54:55] offset:224

;     ...
;       for (int i = 0; i < 8; ++i) { const int kk = 8 * i + (lane >> 3); wv[i] = *(const f32x4*)(W + (size_t)(k0 + kk) * N + n0 + 4 * (lane & 7)); gv[i] = gain ? gain[k0 + kk] : 1.0f; }
; __device__ __forceinline__ void convert_item(const Args& a, int set, int it, LAS float* scr, int lane) {
;     ...
;     if (r < I_UP) { p0_transpose_item(a.in[I_F2W1], D, FF, a.in[I_F2N], (bf16_t*)(ws + WS_W13_2), 1, scr, r, lane); return; } r -= I_UP;
.LBB0_109:
	s_andn2_b64 vcc, exec, s[8:9]
	s_cbranch_vccnz .LBB0_127
	s_add_i32 s8, s93, 0xf600
	s_and_b32 s9, s8, 0xffff
	s_mul_i32 s9, s9, 0xba2f
	s_lshr_b32 s22, s9, 16
	s_lshr_b32 s9, s9, 22
	s_mulk_i32 s9, 0x58
	s_sub_i32 s8, s8, s9
	s_and_b32 s27, s8, 0xffff
	s_and_b32 s26, s22, 0xffc0
	s_lshl_b32 s22, s27, 7
	v_or_b32_e32 v32, s26, v140
	v_lshl_add_u64 v[30:31], v[62:63], 0, s[22:23]
	v_mad_u64_u32 v[2:3], s[8:9], v32, s87, v[30:31]
	s_waitcnt lgkmcnt(3)
	global_load_dwordx4 v[2:5], v[2:3], off nt
	s_waitcnt lgkmcnt(2)
	v_cndmask_b32_e64 v6, 0, 1, s[18:19]
	v_mov_b32_e32 v34, 1.0
	v_cmp_ne_u32_e64 s[8:9], 1, v6
	s_andn2_b64 vcc, exec, s[18:19]
	v_lshlrev_b32_e32 v131, 2, v32
	v_mov_b32_e32 v126, 1.0
	s_cbranch_vccnz .LBB0_112
	global_load_dword v126, v131, s[54:55]

;     ...
;       for (int i = 0; i < 8; ++i) { const int kk = 8 * i + (lane >> 3); wv[i] = *(const f32x4*)(W + (size_t)(k0 + kk) * N + n0 + 4 * (lane & 7)); gv[i] = gain ? gain[k0 + kk] : 1.0f; }
.LBB0_124:
	v_or_b32_e32 v32, 56, v32
	v_mad_u64_u32 v[30:31], s[62:63], v32, s87, v[30:31]
	global_load_dwordx4 v[30:33], v[30:31], off nt
	s_and_b64 vcc, exec, s[8:9]
	s_cbranch_vccnz .LBB0_126
	global_load_dword v132, v131, s[54:55] offset:224

; #define LAS __attribute__((address_space(3)))
; __device__ __forceinline__ unsigned pk2(float lo, float hi) { f32x2 v = {lo, hi}; bf2_t b = __builtin_convertvector(v, bf2_t); return __builtin_bit_cast(unsigned, b); }
;     ...
;       for (int i = 0; i < 8; ++i) { const int kk = 8 * i + (lane >> 3); wv[i] = *(const f32x4*)(W + (size_t)(k0 + kk) * N + n0 + 4 * (lane & 7)); gv[i] = gain ? gain[k0 + kk] : 1.0f; }
; #pragma unroll
;       for (int i = 0; i < 8; ++i) { const int kk = 8 * i + (lane >> 3); LAS float* d = scr + kk * 33 + 4 * (lane & 7); d[0] = wv[i][0] * gv[i]; d[1] = wv[i][1] * gv[i]; d[2] = wv[i][2] * gv[i]; d[3] = wv[i][3] * gv[i]; } }
;     asm volatile("s_waitcnt lgkmcnt(0)" ::: "memory");
;     const int c = lane & 7; const int r0 = dst_row(dmode, n0);
; #pragma unroll
;     for (int j = 0; j < 4; ++j) { const int n = (lane >> 3) + 8 * j; const LAS float* s = scr + (8 * c) * 33 + n;
;         u32x4 o; o.x = pk2(s[0 * 33], s[1 * 33]); o.y = pk2(s[2 * 33], s[3 * 33]); o.z = pk2(s[4 * 33], s[5 * 33]); o.w = pk2(s[6 * 33], s[7 * 33]);
;         *(u32x4*)(WT + (size_t)(r0 + n) * pitch + k0 + 8 * c) = o; }
.LBB0_128:
	s_andn2_b64 vcc, exec, s[8:9]
	s_cbranch_vccnz .LBB0_130
	s_add_i32 s8, s79, 0x1f000
	s_and_b32 s8, s8, 0x1ffc0
	s_and_b32 s9, s13, 0x3e0
	s_waitcnt lgkmcnt(3)
	v_or_b32_e32 v4, s8, v140
	s_lshl_b32 s22, s9, 2
	v_lshl_add_u64 v[2:3], v[64:65], 0, s[22:23]
	v_lshlrev_b32_e32 v34, 12, v4
	v_lshl_add_u64 v[30:31], v[2:3], 0, v[34:35]
	s_waitcnt lgkmcnt(2)
	v_add_co_u32_e32 v6, vcc, 0x8000, v30
	v_add_u32_e32 v124, v105, v141
	s_nop 0
	v_addc_co_u32_e32 v7, vcc, 0, v31, vcc
	v_add_co_u32_e32 v10, vcc, 0x10000, v30
	global_load_dwordx4 v[2:5], v[30:31], off nt
	s_waitcnt lgkmcnt(0)
	global_load_dwordx4 v[6:9], v[6:7], off nt
	v_addc_co_u32_e32 v11, vcc, 0, v31, vcc
	v_add_co_u32_e32 v14, vcc, 0x18000, v30
	v_add_u32_e32 v126, 0x420, v124
	s_nop 0
	v_addc_co_u32_e32 v15, vcc, 0, v31, vcc
	v_add_co_u32_e32 v18, vcc, s71, v30
	global_load_dwordx4 v[10:13], v[10:11], off nt
	s_nop 0
	global_load_dwordx4 v[14:17], v[14:15], off nt
	v_addc_co_u32_e32 v19, vcc, 0, v31, vcc
	v_add_co_u32_e32 v22, vcc, 0x28000, v30
	v_add_u32_e32 v128, 0x428, v124
	s_nop 0
	v_addc_co_u32_e32 v23, vcc, 0, v31, vcc
	global_load_dwordx4 v[18:21], v[18:19], off nt
	s_nop 0
	global_load_dwordx4 v[22:25], v[22:23], off nt
	v_add_co_u32_e32 v26, vcc, 0x30000, v30
	v_add_u32_e32 v132, 0x840, v124
	s_nop 0
	v_addc_co_u32_e32 v27, vcc, 0, v31, vcc
	global_load_dwordx4 v[26:29], v[26:27], off nt
	v_add_co_u32_e32 v30, vcc, 0x38000, v30
	v_add_u32_e32 v134, 0x848, v124
	s_nop 0
	v_addc_co_u32_e32 v31, vcc, 0, v31, vcc
	global_load_dwordx4 v[30:33], v[30:31], off nt
	v_add_u32_e32 v136, 0xc60, v124
	v_add_u32_e32 v138, 0xc68, v124
	v_add_u32_e32 v156, 0x1080, v124
	v_add_u32_e32 v157, 0x1088, v124
	v_add_u32_e32 v158, 0x14a0, v124
	v_add_u32_e32 v159, 0x14a8, v124
	v_add_u32_e32 v160, 0x18c0, v124
	v_add_u32_e32 v161, 0x18c8, v124
	v_add_u32_e32 v162, 0x1ce0, v124
	v_add_u32_e32 v163, 0x1ce8, v124
	v_or_b32_e32 v34, s9, v140
	s_lshl_b32 s22, s8, 1
	v_lshl_add_u64 v[130:131], v[66:67], 0, s[22:23]
	v_lshlrev_b32_e32 v34, 11, v34
	s_waitcnt vmcnt(7)
	ds_write2_b32 v124, v2, v3 offset1:1
	ds_write2_b32 v124, v4, v5 offset0:2 offset1:3
	s_waitcnt vmcnt(6)
	ds_write2_b32 v126, v6, v7 offset1:1
	ds_write2_b32 v128, v8, v9 offset1:1
	s_waitcnt vmcnt(5)
	ds_write2_b32 v132, v10, v11 offset1:1
	ds_write2_b32 v134, v12, v13 offset1:1
	s_waitcnt vmcnt(4)
	ds_write2_b32 v136, v14, v15 offset1:1
	ds_write2_b32 v138, v16, v17 offset1:1
	s_waitcnt vmcnt(3)
	ds_write2_b32 v156, v18, v19 offset1:1
	ds_write2_b32 v157, v20, v21 offset1:1
	s_waitcnt vmcnt(2)
	ds_write2_b32 v158, v22, v23 offset1:1
	ds_write2_b32 v159, v24, v25 offset1:1
	s_waitcnt vmcnt(1)
	ds_write2_b32 v160, v26, v27 offset1:1
	ds_write2_b32 v161, v28, v29 offset1:1
	s_waitcnt vmcnt(0)
	ds_write2_b32 v162, v30, v31 offset1:1
	ds_write2_b32 v163, v32, v33 offset1:1
	s_waitcnt lgkmcnt(0)
	ds_read2_b32 v[6:7], v155 offset0:33 offset1:41
	ds_read2_b32 v[8:9], v155 offset1:8
	ds_read2_b32 v[10:11], v155 offset0:66 offset1:74
	ds_read2_b32 v[12:13], v155 offset0:99 offset1:107
	ds_read2_b32 v[14:15], v155 offset0:132 offset1:140
	ds_read2_b32 v[16:17], v155 offset0:165 offset1:173
	ds_read2_b32 v[18:19], v155 offset0:198 offset1:206
	ds_read2_b32 v[20:21], v155 offset0:231 offset1:239
	v_lshl_add_u64 v[22:23], v[130:131], 0, v[34:35]
	s_waitcnt lgkmcnt(6)
	v_cvt_pk_bf16_f32 v2, v8, v6
	s_waitcnt lgkmcnt(4)
	v_cvt_pk_bf16_f32 v3, v10, v12
	s_waitcnt lgkmcnt(2)
	v_cvt_pk_bf16_f32 v4, v14, v16
	s_waitcnt lgkmcnt(0)
	v_cvt_pk_bf16_f32 v5, v18, v20
	global_store_dwordx4 v[22:23], v[2:5], off sc1
	v_cvt_pk_bf16_f32 v6, v9, v7
	v_cvt_pk_bf16_f32 v7, v11, v13
	v_cvt_pk_bf16_f32 v8, v15, v17
	v_cvt_pk_bf16_f32 v9, v19, v21
	v_or_b32_e32 v2, s9, v142
	ds_read2_b32 v[10:11], v155 offset0:49 offset1:57
	ds_read2_b32 v[12:13], v155 offset0:16 offset1:24
	ds_read2_b32 v[14:15], v155 offset0:82 offset1:90
	ds_read2_b32 v[16:17], v155 offset0:115 offset1:123
	ds_read2_b32 v[18:19], v155 offset0:148 offset1:156
	ds_read2_b32 v[20:21], v155 offset0:181 offset1:189
	ds_read2_b32 v[22:23], v155 offset0:214 offset1:222
	ds_read2_b32 v[24:25], v155 offset0:247 offset1:255
	v_lshlrev_b32_e32 v34, 11, v2
	v_lshl_add_u64 v[2:3], v[130:131], 0, v[34:35]
	global_store_dwordx4 v[2:3], v[6:9], off sc1
	s_waitcnt lgkmcnt(6)
	v_cvt_pk_bf16_f32 v2, v12, v10
	s_waitcnt lgkmcnt(4)
	v_cvt_pk_bf16_f32 v3, v14, v16
	v_or_b32_e32 v6, s9, v143
	v_lshlrev_b32_e32 v34, 11, v6
	s_waitcnt lgkmcnt(2)
	v_cvt_pk_bf16_f32 v4, v18, v20
	s_waitcnt lgkmcnt(0)
	v_cvt_pk_bf16_f32 v5, v22, v24
	v_lshl_add_u64 v[6:7], v[130:131], 0, v[34:35]
	global_store_dwordx4 v[6:7], v[2:5], off sc1
	v_or_b32_e32 v6, s9, v144
	v_lshlrev_b32_e32 v34, 11, v6
	v_cvt_pk_bf16_f32 v2, v13, v11
	v_cvt_pk_bf16_f32 v3, v15, v17
	v_cvt_pk_bf16_f32 v4, v19, v21
	v_cvt_pk_bf16_f32 v5, v23, v25
	v_lshl_add_u64 v[6:7], v[130:131], 0, v[34:35]
	global_store_dwordx4 v[6:7], v[2:5], off sc1
	s_waitcnt lgkmcnt(0)

; #define LAS __attribute__((address_space(3)))
; __device__ __forceinline__ unsigned pk2(float lo, float hi) { f32x2 v = {lo, hi}; bf2_t b = __builtin_convertvector(v, bf2_t); return __builtin_bit_cast(unsigned, b); }
;     ...
;       for (int i = 0; i < 8; ++i) { const int kk = 8 * i + (lane >> 3); wv[i] = *(const f32x4*)(W + (size_t)(k0 + kk) * N + n0 + 4 * (lane & 7)); gv[i] = gain ? gain[k0 + kk] : 1.0f; }
; #pragma unroll
;       for (int i = 0; i < 8; ++i) { const int kk = 8 * i + (lane >> 3); LAS float* d = scr + kk * 33 + 4 * (lane & 7); d[0] = wv[i][0] * gv[i]; d[1] = wv[i][1] * gv[i]; d[2] = wv[i][2] * gv[i]; d[3] = wv[i][3] * gv[i]; } }
;     asm volatile("s_waitcnt lgkmcnt(0)" ::: "memory");
;     const int c = lane & 7; const int r0 = dst_row(dmode, n0);
; #pragma unroll
;     for (int j = 0; j < 4; ++j) { const int n = (lane >> 3) + 8 * j; const LAS float* s = scr + (8 * c) * 33 + n;
;         u32x4 o; o.x = pk2(s[0 * 33], s[1 * 33]); o.y = pk2(s[2 * 33], s[3 * 33]); o.z = pk2(s[4 * 33], s[5 * 33]); o.w = pk2(s[6 * 33], s[7 * 33]);
;         *(u32x4*)(WT + (size_t)(r0 + n) * pitch + k0 + 8 * c) = o; }
.LBB0_131:
	s_andn2_b64 vcc, exec, s[8:9]
	s_cbranch_vccnz .LBB0_133
	s_and_b32 s8, s79, 0x1c0
	s_and_b32 s9, s13, 0x3e0
	s_waitcnt lgkmcnt(3)
	v_bitop3_b32 v4, s8, v140, v154 bitop3:0xde
	s_lshl_b32 s22, s9, 2
	v_lshl_add_u64 v[2:3], v[86:87], 0, s[22:23]
	v_lshlrev_b32_e32 v34, 12, v4
	v_lshl_add_u64 v[30:31], v[2:3], 0, v[34:35]
	s_waitcnt lgkmcnt(2)
	v_add_co_u32_e32 v6, vcc, 0x8000, v30
	v_add_u32_e32 v124, v105, v141
	s_nop 0
	v_addc_co_u32_e32 v7, vcc, 0, v31, vcc
	v_add_co_u32_e32 v10, vcc, 0x10000, v30
	global_load_dwordx4 v[2:5], v[30:31], off nt
	s_waitcnt lgkmcnt(0)
	global_load_dwordx4 v[6:9], v[6:7], off nt
	v_addc_co_u32_e32 v11, vcc, 0, v31, vcc
	v_add_co_u32_e32 v14, vcc, 0x18000, v30
	v_add_u32_e32 v126, 0x420, v124
	s_nop 0
	v_addc_co_u32_e32 v15, vcc, 0, v31, vcc
	v_add_co_u32_e32 v18, vcc, s71, v30
	global_load_dwordx4 v[10:13], v[10:11], off nt
	s_nop 0
	global_load_dwordx4 v[14:17], v[14:15], off nt
	v_addc_co_u32_e32 v19, vcc, 0, v31, vcc
	v_add_co_u32_e32 v22, vcc, 0x28000, v30
	v_add_u32_e32 v128, 0x428, v124
	s_nop 0
	v_addc_co_u32_e32 v23, vcc, 0, v31, vcc
	global_load_dwordx4 v[18:21], v[18:19], off nt
	s_nop 0
	global_load_dwordx4 v[22:25], v[22:23], off nt
	v_add_co_u32_e32 v26, vcc, 0x30000, v30
	v_add_u32_e32 v132, 0x840, v124
	s_nop 0
	v_addc_co_u32_e32 v27, vcc, 0, v31, vcc
	global_load_dwordx4 v[26:29], v[26:27], off nt
	v_add_co_u32_e32 v30, vcc, 0x38000, v30
	v_add_u32_e32 v134, 0x848, v124
	s_nop 0
	v_addc_co_u32_e32 v31, vcc, 0, v31, vcc
	global_load_dwordx4 v[30:33], v[30:31], off nt
	v_add_u32_e32 v136, 0xc60, v124
	v_add_u32_e32 v138, 0xc68, v124
	v_add_u32_e32 v156, 0x1080, v124
	v_add_u32_e32 v157, 0x1088, v124
	v_add_u32_e32 v158, 0x14a0, v124
	v_add_u32_e32 v159, 0x14a8, v124
	v_add_u32_e32 v160, 0x18c0, v124
	v_add_u32_e32 v161, 0x18c8, v124
	v_add_u32_e32 v162, 0x1ce0, v124
	v_add_u32_e32 v163, 0x1ce8, v124
	s_xor_b32 s8, s8, 0x100
	v_or_b32_e32 v34, s9, v140
	s_lshl_b32 s22, s8, 1
	v_lshl_add_u64 v[130:131], v[68:69], 0, s[22:23]
	v_lshlrev_b32_e32 v34, 10, v34
	s_waitcnt vmcnt(7)
	ds_write2_b32 v124, v2, v3 offset1:1
	ds_write2_b32 v124, v4, v5 offset0:2 offset1:3
	s_waitcnt vmcnt(6)
	ds_write2_b32 v126, v6, v7 offset1:1
	ds_write2_b32 v128, v8, v9 offset1:1
	s_waitcnt vmcnt(5)
	ds_write2_b32 v132, v10, v11 offset1:1
	ds_write2_b32 v134, v12, v13 offset1:1
	s_waitcnt vmcnt(4)
	ds_write2_b32 v136, v14, v15 offset1:1
	ds_write2_b32 v138, v16, v17 offset1:1
	s_waitcnt vmcnt(3)
	ds_write2_b32 v156, v18, v19 offset1:1
	ds_write2_b32 v157, v20, v21 offset1:1
	s_waitcnt vmcnt(2)
	ds_write2_b32 v158, v22, v23 offset1:1
	ds_write2_b32 v159, v24, v25 offset1:1
	s_waitcnt vmcnt(1)
	ds_write2_b32 v160, v26, v27 offset1:1
	ds_write2_b32 v161, v28, v29 offset1:1
	s_waitcnt vmcnt(0)
	ds_write2_b32 v162, v30, v31 offset1:1
	ds_write2_b32 v163, v32, v33 offset1:1
	s_waitcnt lgkmcnt(0)
	ds_read2_b32 v[6:7], v155 offset0:33 offset1:41
	ds_read2_b32 v[8:9], v155 offset1:8
	ds_read2_b32 v[10:11], v155 offset0:66 offset1:74
	ds_read2_b32 v[12:13], v155 offset0:99 offset1:107
	ds_read2_b32 v[14:15], v155 offset0:132 offset1:140
	ds_read2_b32 v[16:17], v155 offset0:165 offset1:173
	ds_read2_b32 v[18:19], v155 offset0:198 offset1:206
	ds_read2_b32 v[20:21], v155 offset0:231 offset1:239
	v_lshl_add_u64 v[22:23], v[130:131], 0, v[34:35]
	s_waitcnt lgkmcnt(6)
	v_cvt_pk_bf16_f32 v2, v8, v6
	s_waitcnt lgkmcnt(4)
	v_cvt_pk_bf16_f32 v3, v10, v12
	s_waitcnt lgkmcnt(2)
	v_cvt_pk_bf16_f32 v4, v14, v16
	s_waitcnt lgkmcnt(0)
	v_cvt_pk_bf16_f32 v5, v18, v20
	global_store_dwordx4 v[22:23], v[2:5], off sc1
	v_or_b32_e32 v6, s9, v142
	v_lshlrev_b32_e32 v34, 10, v6
	v_cvt_pk_bf16_f32 v2, v9, v7
	v_cvt_pk_bf16_f32 v3, v11, v13
	v_cvt_pk_bf16_f32 v4, v15, v17
	v_cvt_pk_bf16_f32 v5, v19, v21
	ds_read2_b32 v[8:9], v155 offset0:49 offset1:57
	ds_read2_b32 v[10:11], v155 offset0:16 offset1:24
	ds_read2_b32 v[12:13], v155 offset0:82 offset1:90
	ds_read2_b32 v[14:15], v155 offset0:115 offset1:123
	ds_read2_b32 v[16:17], v155 offset0:148 offset1:156
	ds_read2_b32 v[18:19], v155 offset0:181 offset1:189
	ds_read2_b32 v[20:21], v155 offset0:214 offset1:222
	ds_read2_b32 v[22:23], v155 offset0:247 offset1:255
	v_lshl_add_u64 v[6:7], v[130:131], 0, v[34:35]
	global_store_dwordx4 v[6:7], v[2:5], off sc1
	v_or_b32_e32 v6, s9, v143
	v_lshlrev_b32_e32 v34, 10, v6
	s_waitcnt lgkmcnt(6)
	v_cvt_pk_bf16_f32 v2, v10, v8
	s_waitcnt lgkmcnt(4)
	v_cvt_pk_bf16_f32 v3, v12, v14
	s_waitcnt lgkmcnt(2)
	v_cvt_pk_bf16_f32 v4, v16, v18
	s_waitcnt lgkmcnt(0)
	v_cvt_pk_bf16_f32 v5, v20, v22
	v_lshl_add_u64 v[6:7], v[130:131], 0, v[34:35]
	global_store_dwordx4 v[6:7], v[2:5], off sc1
	v_or_b32_e32 v6, s9, v144
	v_lshlrev_b32_e32 v34, 10, v6
	v_cvt_pk_bf16_f32 v2, v11, v9
	v_cvt_pk_bf16_f32 v3, v13, v15
	v_cvt_pk_bf16_f32 v4, v17, v19
	v_cvt_pk_bf16_f32 v5, v21, v23
	v_lshl_add_u64 v[6:7], v[130:131], 0, v[34:35]
	global_store_dwordx4 v[6:7], v[2:5], off sc1
	s_waitcnt lgkmcnt(0)

; #define LAS __attribute__((address_space(3)))
; __device__ __forceinline__ unsigned pk2(float lo, float hi) { f32x2 v = {lo, hi}; bf2_t b = __builtin_convertvector(v, bf2_t); return __builtin_bit_cast(unsigned, b); }
;     ...
;       for (int i = 0; i < 8; ++i) { const int kk = 8 * i + (lane >> 3); wv[i] = *(const f32x4*)(W + (size_t)(k0 + kk) * N + n0 + 4 * (lane & 7)); gv[i] = gain ? gain[k0 + kk] : 1.0f; }
; #pragma unroll
;       for (int i = 0; i < 8; ++i) { const int kk = 8 * i + (lane >> 3); LAS float* d = scr + kk * 33 + 4 * (lane & 7); d[0] = wv[i][0] * gv[i]; d[1] = wv[i][1] * gv[i]; d[2] = wv[i][2] * gv[i]; d[3] = wv[i][3] * gv[i]; } }
;     asm volatile("s_waitcnt lgkmcnt(0)" ::: "memory");
;     const int c = lane & 7; const int r0 = dst_row(dmode, n0);
; #pragma unroll
;     for (int j = 0; j < 4; ++j) { const int n = (lane >> 3) + 8 * j; const LAS float* s = scr + (8 * c) * 33 + n;
;         u32x4 o; o.x = pk2(s[0 * 33], s[1 * 33]); o.y = pk2(s[2 * 33], s[3 * 33]); o.z = pk2(s[4 * 33], s[5 * 33]); o.w = pk2(s[6 * 33], s[7 * 33]);
;         *(u32x4*)(WT + (size_t)(r0 + n) * pitch + k0 + 8 * c) = o; }
.LBB0_134:
	s_andn2_b64 vcc, exec, s[8:9]
	s_cbranch_vccnz .LBB0_136
	s_and_b32 s8, s79, 0x1c0
	s_and_b32 s9, s13, 0x3e0
	s_waitcnt lgkmcnt(3)
	v_or_b32_e32 v4, s8, v140
	s_lshl_b32 s22, s9, 2
	v_lshl_add_u64 v[2:3], v[88:89], 0, s[22:23]
	v_lshlrev_b32_e32 v34, 12, v4
	v_lshl_add_u64 v[30:31], v[2:3], 0, v[34:35]
	s_waitcnt lgkmcnt(2)
	v_add_co_u32_e32 v6, vcc, 0x8000, v30
	v_add_u32_e32 v124, v105, v141
	s_nop 0
	v_addc_co_u32_e32 v7, vcc, 0, v31, vcc
	v_add_co_u32_e32 v10, vcc, 0x10000, v30
	global_load_dwordx4 v[2:5], v[30:31], off nt
	s_waitcnt lgkmcnt(0)
	global_load_dwordx4 v[6:9], v[6:7], off nt
	v_addc_co_u32_e32 v11, vcc, 0, v31, vcc
	v_add_co_u32_e32 v14, vcc, 0x18000, v30
	v_add_u32_e32 v126, 0x420, v124
	s_nop 0
	v_addc_co_u32_e32 v15, vcc, 0, v31, vcc
	v_add_co_u32_e32 v18, vcc, s71, v30
	global_load_dwordx4 v[10:13], v[10:11], off nt
	s_nop 0
	global_load_dwordx4 v[14:17], v[14:15], off nt
	v_addc_co_u32_e32 v19, vcc, 0, v31, vcc
	v_add_co_u32_e32 v22, vcc, 0x28000, v30
	v_add_u32_e32 v128, 0x428, v124
	s_nop 0
	v_addc_co_u32_e32 v23, vcc, 0, v31, vcc
	global_load_dwordx4 v[18:21], v[18:19], off nt
	s_nop 0
	global_load_dwordx4 v[22:25], v[22:23], off nt
	v_add_co_u32_e32 v26, vcc, 0x30000, v30
	v_add_u32_e32 v132, 0x840, v124
	s_nop 0
	v_addc_co_u32_e32 v27, vcc, 0, v31, vcc
	global_load_dwordx4 v[26:29], v[26:27], off nt
	v_add_co_u32_e32 v30, vcc, 0x38000, v30
	v_add_u32_e32 v134, 0x848, v124
	s_nop 0
	v_addc_co_u32_e32 v31, vcc, 0, v31, vcc
	global_load_dwordx4 v[30:33], v[30:31], off nt
	v_add_u32_e32 v136, 0xc60, v124
	v_add_u32_e32 v138, 0xc68, v124
	v_add_u32_e32 v156, 0x1080, v124
	v_add_u32_e32 v157, 0x1088, v124
	v_add_u32_e32 v158, 0x14a0, v124
	v_add_u32_e32 v159, 0x14a8, v124
	v_add_u32_e32 v160, 0x18c0, v124
	v_add_u32_e32 v161, 0x18c8, v124
	v_add_u32_e32 v162, 0x1ce0, v124
	v_add_u32_e32 v163, 0x1ce8, v124
	v_or_b32_e32 v34, s9, v140
	s_lshl_b32 s22, s8, 1
	v_lshl_add_u64 v[130:131], v[70:71], 0, s[22:23]
	v_lshlrev_b32_e32 v34, 10, v34
	s_waitcnt vmcnt(7)
	ds_write2_b32 v124, v2, v3 offset1:1
	ds_write2_b32 v124, v4, v5 offset0:2 offset1:3
	s_waitcnt vmcnt(6)
	ds_write2_b32 v126, v6, v7 offset1:1
	ds_write2_b32 v128, v8, v9 offset1:1
	s_waitcnt vmcnt(5)
	ds_write2_b32 v132, v10, v11 offset1:1
	ds_write2_b32 v134, v12, v13 offset1:1
	s_waitcnt vmcnt(4)
	ds_write2_b32 v136, v14, v15 offset1:1
	ds_write2_b32 v138, v16, v17 offset1:1
	s_waitcnt vmcnt(3)
	ds_write2_b32 v156, v18, v19 offset1:1
	ds_write2_b32 v157, v20, v21 offset1:1
	s_waitcnt vmcnt(2)
	ds_write2_b32 v158, v22, v23 offset1:1
	ds_write2_b32 v159, v24, v25 offset1:1
	s_waitcnt vmcnt(1)
	ds_write2_b32 v160, v26, v27 offset1:1
	ds_write2_b32 v161, v28, v29 offset1:1
	s_waitcnt vmcnt(0)
	ds_write2_b32 v162, v30, v31 offset1:1
	ds_write2_b32 v163, v32, v33 offset1:1
	s_waitcnt lgkmcnt(0)
	ds_read2_b32 v[6:7], v155 offset0:33 offset1:41
	ds_read2_b32 v[8:9], v155 offset1:8
	ds_read2_b32 v[10:11], v155 offset0:66 offset1:74
	ds_read2_b32 v[12:13], v155 offset0:99 offset1:107
	ds_read2_b32 v[14:15], v155 offset0:132 offset1:140
	ds_read2_b32 v[16:17], v155 offset0:165 offset1:173
	ds_read2_b32 v[18:19], v155 offset0:198 offset1:206
	ds_read2_b32 v[20:21], v155 offset0:231 offset1:239
	v_lshl_add_u64 v[22:23], v[130:131], 0, v[34:35]
	s_waitcnt lgkmcnt(6)
	v_cvt_pk_bf16_f32 v2, v8, v6
	s_waitcnt lgkmcnt(4)
	v_cvt_pk_bf16_f32 v3, v10, v12
	s_waitcnt lgkmcnt(2)
	v_cvt_pk_bf16_f32 v4, v14, v16
	s_waitcnt lgkmcnt(0)
	v_cvt_pk_bf16_f32 v5, v18, v20
	global_store_dwordx4 v[22:23], v[2:5], off sc1
	v_cvt_pk_bf16_f32 v6, v9, v7
	v_cvt_pk_bf16_f32 v7, v11, v13
	v_cvt_pk_bf16_f32 v8, v15, v17
	v_cvt_pk_bf16_f32 v9, v19, v21
	v_or_b32_e32 v2, s9, v142
	ds_read2_b32 v[10:11], v155 offset0:49 offset1:57
	ds_read2_b32 v[12:13], v155 offset0:16 offset1:24
	ds_read2_b32 v[14:15], v155 offset0:82 offset1:90
	ds_read2_b32 v[16:17], v155 offset0:115 offset1:123
	ds_read2_b32 v[18:19], v155 offset0:148 offset1:156
	ds_read2_b32 v[20:21], v155 offset0:181 offset1:189
	ds_read2_b32 v[22:23], v155 offset0:214 offset1:222
	ds_read2_b32 v[24:25], v155 offset0:247 offset1:255
	v_lshlrev_b32_e32 v34, 10, v2
	v_lshl_add_u64 v[2:3], v[130:131], 0, v[34:35]
	global_store_dwordx4 v[2:3], v[6:9], off sc1
	s_waitcnt lgkmcnt(6)
	v_cvt_pk_bf16_f32 v2, v12, v10
	s_waitcnt lgkmcnt(4)
	v_cvt_pk_bf16_f32 v3, v14, v16
	v_or_b32_e32 v6, s9, v143
	v_lshlrev_b32_e32 v34, 10, v6
	s_waitcnt lgkmcnt(2)
	v_cvt_pk_bf16_f32 v4, v18, v20
	s_waitcnt lgkmcnt(0)
	v_cvt_pk_bf16_f32 v5, v22, v24
	v_lshl_add_u64 v[6:7], v[130:131], 0, v[34:35]
	global_store_dwordx4 v[6:7], v[2:5], off sc1
	v_or_b32_e32 v6, s9, v144
	v_lshlrev_b32_e32 v34, 10, v6
	v_cvt_pk_bf16_f32 v2, v13, v11
	v_cvt_pk_bf16_f32 v3, v15, v17
	v_cvt_pk_bf16_f32 v4, v19, v21
	v_cvt_pk_bf16_f32 v5, v23, v25
	v_lshl_add_u64 v[6:7], v[130:131], 0, v[34:35]
	global_store_dwordx4 v[6:7], v[2:5], off sc1
	s_waitcnt lgkmcnt(0)

; #define LAS __attribute__((address_space(3)))
; __device__ __forceinline__ unsigned pk2(float lo, float hi) { f32x2 v = {lo, hi}; bf2_t b = __builtin_convertvector(v, bf2_t); return __builtin_bit_cast(unsigned, b); }
;     ...
;     { f32x4 wv[8]; float gv[8];
; #pragma unroll
;       for (int i = 0; i < 8; ++i) { const int kk = 8 * i + (lane >> 3); wv[i] = *(const f32x4*)(W + (size_t)(k0 + kk) * N + n0 + 4 * (lane & 7)); gv[i] = gain ? gain[k0 + kk] : 1.0f; }
; #pragma unroll
;       for (int i = 0; i < 8; ++i) { const int kk = 8 * i + (lane >> 3); LAS float* d = scr + kk * 33 + 4 * (lane & 7); d[0] = wv[i][0] * gv[i]; d[1] = wv[i][1] * gv[i]; d[2] = wv[i][2] * gv[i]; d[3] = wv[i][3] * gv[i]; } }
;     asm volatile("s_waitcnt lgkmcnt(0)" ::: "memory");
;     const int c = lane & 7; const int r0 = dst_row(dmode, n0);
; #pragma unroll
;     for (int j = 0; j < 4; ++j) { const int n = (lane >> 3) + 8 * j; const LAS float* s = scr + (8 * c) * 33 + n;
;         u32x4 o; o.x = pk2(s[0 * 33], s[1 * 33]); o.y = pk2(s[2 * 33], s[3 * 33]); o.z = pk2(s[4 * 33], s[5 * 33]); o.w = pk2(s[6 * 33], s[7 * 33]);
;         *(u32x4*)(WT + (size_t)(r0 + n) * pitch + k0 + 8 * c) = o; }
.LBB0_137:
	s_andn2_b64 vcc, exec, s[8:9]
	s_cbranch_vccnz .LBB0_139
	s_and_b32 s8, s79, 0x1c0
	s_and_b32 s9, s13, 0x3e0
	s_waitcnt lgkmcnt(3)
	v_or_b32_e32 v4, s8, v140
	s_lshl_b32 s22, s9, 2
	v_lshl_add_u64 v[2:3], v[90:91], 0, s[22:23]
	v_lshlrev_b32_e32 v34, 12, v4
	v_lshl_add_u64 v[30:31], v[2:3], 0, v[34:35]
	s_waitcnt lgkmcnt(2)
	v_add_co_u32_e32 v6, vcc, 0x8000, v30
	v_add_u32_e32 v124, v105, v141
	s_nop 0
	v_addc_co_u32_e32 v7, vcc, 0, v31, vcc
	v_add_co_u32_e32 v10, vcc, 0x10000, v30
	global_load_dwordx4 v[2:5], v[30:31], off nt
	s_waitcnt lgkmcnt(0)
	global_load_dwordx4 v[6:9], v[6:7], off nt
	v_addc_co_u32_e32 v11, vcc, 0, v31, vcc
	v_add_co_u32_e32 v14, vcc, 0x18000, v30
	v_add_u32_e32 v126, 0x420, v124
	s_nop 0
	v_addc_co_u32_e32 v15, vcc, 0, v31, vcc
	v_add_co_u32_e32 v18, vcc, s71, v30
	global_load_dwordx4 v[10:13], v[10:11], off nt
	s_nop 0
	global_load_dwordx4 v[14:17], v[14:15], off nt
	v_addc_co_u32_e32 v19, vcc, 0, v31, vcc
	v_add_co_u32_e32 v22, vcc, 0x28000, v30
	v_add_u32_e32 v128, 0x428, v124
	s_nop 0
	v_addc_co_u32_e32 v23, vcc, 0, v31, vcc
	global_load_dwordx4 v[18:21], v[18:19], off nt
	s_nop 0
	global_load_dwordx4 v[22:25], v[22:23], off nt
	v_add_co_u32_e32 v26, vcc, 0x30000, v30
	v_add_u32_e32 v132, 0x840, v124
	s_nop 0
	v_addc_co_u32_e32 v27, vcc, 0, v31, vcc
	global_load_dwordx4 v[26:29], v[26:27], off nt
	v_add_co_u32_e32 v30, vcc, 0x38000, v30
	v_add_u32_e32 v134, 0x848, v124
	s_nop 0
	v_addc_co_u32_e32 v31, vcc, 0, v31, vcc
	global_load_dwordx4 v[30:33], v[30:31], off nt
	v_add_u32_e32 v136, 0xc60, v124
	v_add_u32_e32 v138, 0xc68, v124
	v_add_u32_e32 v156, 0x1080, v124
	v_add_u32_e32 v157, 0x1088, v124
	v_add_u32_e32 v158, 0x14a0, v124
	v_add_u32_e32 v159, 0x14a8, v124
	v_add_u32_e32 v160, 0x18c0, v124
	v_add_u32_e32 v161, 0x18c8, v124
	v_add_u32_e32 v162, 0x1ce0, v124
	v_add_u32_e32 v163, 0x1ce8, v124
	v_or_b32_e32 v34, s9, v140
	s_lshl_b32 s22, s8, 1
	v_lshl_add_u64 v[130:131], v[82:83], 0, s[22:23]
	v_lshlrev_b32_e32 v34, 10, v34
	s_waitcnt vmcnt(7)
	ds_write2_b32 v124, v2, v3 offset1:1
	ds_write2_b32 v124, v4, v5 offset0:2 offset1:3
	s_waitcnt vmcnt(6)
	ds_write2_b32 v126, v6, v7 offset1:1
	ds_write2_b32 v128, v8, v9 offset1:1
	s_waitcnt vmcnt(5)
	ds_write2_b32 v132, v10, v11 offset1:1
	ds_write2_b32 v134, v12, v13 offset1:1
	s_waitcnt vmcnt(4)
	ds_write2_b32 v136, v14, v15 offset1:1
	ds_write2_b32 v138, v16, v17 offset1:1
	s_waitcnt vmcnt(3)
	ds_write2_b32 v156, v18, v19 offset1:1
	ds_write2_b32 v157, v20, v21 offset1:1
	s_waitcnt vmcnt(2)
	ds_write2_b32 v158, v22, v23 offset1:1
	ds_write2_b32 v159, v24, v25 offset1:1
	s_waitcnt vmcnt(1)
	ds_write2_b32 v160, v26, v27 offset1:1
	ds_write2_b32 v161, v28, v29 offset1:1
	s_waitcnt vmcnt(0)
	ds_write2_b32 v162, v30, v31 offset1:1
	ds_write2_b32 v163, v32, v33 offset1:1
	s_waitcnt lgkmcnt(0)
	ds_read2_b32 v[6:7], v155 offset0:33 offset1:41
	ds_read2_b32 v[8:9], v155 offset1:8
	ds_read2_b32 v[10:11], v155 offset0:66 offset1:74
	ds_read2_b32 v[12:13], v155 offset0:99 offset1:107
	ds_read2_b32 v[14:15], v155 offset0:132 offset1:140
	ds_read2_b32 v[16:17], v155 offset0:165 offset1:173
	ds_read2_b32 v[18:19], v155 offset0:198 offset1:206
	ds_read2_b32 v[20:21], v155 offset0:231 offset1:239
	v_lshl_add_u64 v[22:23], v[130:131], 0, v[34:35]
	s_waitcnt lgkmcnt(6)
	v_cvt_pk_bf16_f32 v2, v8, v6
	s_waitcnt lgkmcnt(4)
	v_cvt_pk_bf16_f32 v3, v10, v12
	s_waitcnt lgkmcnt(2)
	v_cvt_pk_bf16_f32 v4, v14, v16
	s_waitcnt lgkmcnt(0)
	v_cvt_pk_bf16_f32 v5, v18, v20
	global_store_dwordx4 v[22:23], v[2:5], off sc1
	v_cvt_pk_bf16_f32 v6, v9, v7
	v_cvt_pk_bf16_f32 v7, v11, v13
	v_cvt_pk_bf16_f32 v8, v15, v17
	v_cvt_pk_bf16_f32 v9, v19, v21
	v_or_b32_e32 v2, s9, v142
	ds_read2_b32 v[10:11], v155 offset0:49 offset1:57
	ds_read2_b32 v[12:13], v155 offset0:16 offset1:24
	ds_read2_b32 v[14:15], v155 offset0:82 offset1:90
	ds_read2_b32 v[16:17], v155 offset0:115 offset1:123
	ds_read2_b32 v[18:19], v155 offset0:148 offset1:156
	ds_read2_b32 v[20:21], v155 offset0:181 offset1:189
	ds_read2_b32 v[22:23], v155 offset0:214 offset1:222
	ds_read2_b32 v[24:25], v155 offset0:247 offset1:255
	v_lshlrev_b32_e32 v34, 10, v2
	v_lshl_add_u64 v[2:3], v[130:131], 0, v[34:35]
	global_store_dwordx4 v[2:3], v[6:9], off sc1
	s_waitcnt lgkmcnt(6)
	v_cvt_pk_bf16_f32 v2, v12, v10
	s_waitcnt lgkmcnt(4)
	v_cvt_pk_bf16_f32 v3, v14, v16
	v_or_b32_e32 v6, s9, v143
	v_lshlrev_b32_e32 v34, 10, v6
	s_waitcnt lgkmcnt(2)
	v_cvt_pk_bf16_f32 v4, v18, v20
	s_waitcnt lgkmcnt(0)
	v_cvt_pk_bf16_f32 v5, v22, v24
	v_lshl_add_u64 v[6:7], v[130:131], 0, v[34:35]
	global_store_dwordx4 v[6:7], v[2:5], off sc1
	v_or_b32_e32 v6, s9, v144
	v_lshlrev_b32_e32 v34, 10, v6
	v_cvt_pk_bf16_f32 v2, v13, v11
	v_cvt_pk_bf16_f32 v3, v15, v17
	v_cvt_pk_bf16_f32 v4, v19, v21
	v_cvt_pk_bf16_f32 v5, v23, v25
	v_lshl_add_u64 v[6:7], v[130:131], 0, v[34:35]
	global_store_dwordx4 v[6:7], v[2:5], off sc1
	s_waitcnt lgkmcnt(0)

; #define LAS __attribute__((address_space(3)))
;     ...
;     { f32x4 wv[8]; float gv[8];
; #pragma unroll
;       for (int i = 0; i < 8; ++i) { const int kk = 8 * i + (lane >> 3); wv[i] = *(const f32x4*)(W + (size_t)(k0 + kk) * N + n0 + 4 * (lane & 7)); gv[i] = gain ? gain[k0 + kk] : 1.0f; }
; #pragma unroll
;       for (int i = 0; i < 8; ++i) { const int kk = 8 * i + (lane >> 3); LAS float* d = scr + kk * 33 + 4 * (lane & 7); d[0] = wv[i][0] * gv[i]; d[1] = wv[i][1] * gv[i]; d[2] = wv[i][2] * gv[i]; d[3] = wv[i][3] * gv[i]; } }
.LBB0_140:
	s_andn2_b64 vcc, exec, s[8:9]
	s_cbranch_vccnz .LBB0_81
	s_mul_hi_i32 s8, s93, 0x2aaaaaab
	s_lshr_b32 s9, s8, 31
	s_ashr_i32 s8, s8, 4
	s_add_i32 s8, s8, s9
	s_lshl_b32 s76, s8, 6
	s_mulk_i32 s8, 0xf400
	s_add_i32 s26, s13, s8
	s_ashr_i32 s27, s26, 31
	v_or_b32_e32 v30, s76, v140
	v_lshl_add_u64 v[32:33], s[26:27], 2, v[92:93]
	v_mad_i64_i32 v[2:3], s[8:9], v30, s88, v[32:33]
	s_waitcnt lgkmcnt(3)
	global_load_dwordx4 v[2:5], v[2:3], off nt
	v_ashrrev_i32_e32 v31, 31, v30
	s_waitcnt lgkmcnt(2)
	v_cndmask_b32_e64 v6, 0, 1, s[36:37]
	v_mov_b32_e32 v34, 1.0
	v_cmp_ne_u32_e64 s[8:9], 1, v6
	s_andn2_b64 vcc, exec, s[36:37]
	v_lshl_add_u64 v[130:131], v[30:31], 2, s[24:25]
	v_mov_b32_e32 v126, 1.0
	s_cbranch_vccnz .LBB0_143
	global_load_dword v126, v[130:131], off
.LBB0_143:
	v_or_b32_e32 v6, 8, v30
	v_mad_i64_i32 v[6:7], s[62:63], v6, s88, v[32:33]
	s_waitcnt lgkmcnt(0)
	global_load_dwordx4 v[6:9], v[6:7], off nt
	s_and_b64 vcc, exec, s[8:9]
	s_cbranch_vccnz .LBB0_145
	global_load_dword v34, v[130:131], off offset:32
.LBB0_145:
	v_or_b32_e32 v10, 16, v30
	v_mad_i64_i32 v[10:11], s[62:63], v10, s88, v[32:33]
	global_load_dwordx4 v[10:13], v[10:11], off nt
	v_mov_b32_e32 v124, 1.0
	s_and_b64 vcc, exec, s[8:9]
	v_mov_b32_e32 v132, 1.0
	s_cbranch_vccnz .LBB0_147
	global_load_dword v132, v[130:131], off offset:64
.LBB0_147:
	v_or_b32_e32 v14, 24, v30
	v_mad_i64_i32 v[14:15], s[62:63], v14, s88, v[32:33]
	global_load_dwordx4 v[14:17], v[14:15], off nt
	s_and_b64 vcc, exec, s[8:9]
	s_cbranch_vccnz .LBB0_149
	global_load_dword v124, v[130:131], off offset:96
.LBB0_149:
	v_or_b32_e32 v18, 32, v30
	v_mad_i64_i32 v[18:19], s[62:63], v18, s88, v[32:33]
	global_load_dwordx4 v[18:21], v[18:19], off nt
	v_mov_b32_e32 v128, 1.0
	s_and_b64 vcc, exec, s[8:9]
	v_mov_b32_e32 v136, 1.0
	s_cbranch_vccnz .LBB0_151
	global_load_dword v136, v[130:131], off offset:128
.LBB0_151:
	v_or_b32_e32 v22, 40, v30
	v_mad_i64_i32 v[22:23], s[62:63], v22, s88, v[32:33]
	global_load_dwordx4 v[22:25], v[22:23], off nt
	s_and_b64 vcc, exec, s[8:9]
	s_cbranch_vccnz .LBB0_153
	global_load_dword v128, v[130:131], off offset:160
.LBB0_153:
	v_or_b32_e32 v26, 48, v30
	v_mad_i64_i32 v[26:27], s[62:63], v26, s88, v[32:33]
	global_load_dwordx4 v[26:29], v[26:27], off nt
	v_mov_b32_e32 v134, 1.0
	s_and_b64 vcc, exec, s[8:9]
	v_mov_b32_e32 v138, 1.0
	s_cbranch_vccnz .LBB0_155
	global_load_dword v138, v[130:131], off offset:192
.LBB0_155:
	v_or_b32_e32 v30, 56, v30
	v_mad_i64_i32 v[30:31], s[62:63], v30, s88, v[32:33]
	global_load_dwordx4 v[30:33], v[30:31], off nt
	s_and_b64 vcc, exec, s[8:9]
	s_cbranch_vccnz .LBB0_80
	global_load_dword v134, v[130:131], off offset:224
	s_branch .LBB0_80

; __device__ __forceinline__ unsigned pk2(float lo, float hi) { f32x2 v = {lo, hi}; bf2_t b = __builtin_convertvector(v, bf2_t); return __builtin_bit_cast(unsigned, b); }
; __device__ __forceinline__ void p0_prologue(const Args& a, LAS unsigned char* lds, int G, bool late_in_p1) {
;     ...
;       for (int m0 = gw; m0 < S; m0 += 2 * NGW) { f32x4 v[2][4];
; #pragma unroll
;           for (int u = 0; u < 2; ++u) { const int m = m0 + u * NGW; const f32x4* xr = (const f32x4*)(x + (size_t)(m < S ? m : m0) * D) + lane;
; #pragma unroll
;               for (int j = 0; j < 4; ++j) v[u][j] = xr[64 * j]; }
; #pragma unroll
;           for (int u = 0; u < 2; ++u) { const int m = m0 + u * NGW; if (m < S) { float s = 0.f;
; #pragma unroll
;               for (int j = 0; j < 4; ++j) s += (v[u][j][0] * v[u][j][0] + v[u][j][1] * v[u][j][1]) + (v[u][j][2] * v[u][j][2] + v[u][j][3] * v[u][j][3]);
;               s = wave_sum(s); if (lane == 0) ssq0[m] = s;
;               u32x2* o8 = (u32x2*)(XB + (size_t)m * D) + lane;
; #pragma unroll
;               for (int j = 0; j < 4; ++j) { u32x2 w; w.x = pk2(v[u][j][0], v[u][j][1]); w.y = pk2(v[u][j][2], v[u][j][3]); o8[64 * j] = w; } } } } }
.LBB0_166:
	s_ashr_i32 s77, s76, 31
	s_lshl_b64 s[8:9], s[76:77], 12
	s_waitcnt vmcnt(4)
	v_lshl_add_u64 v[2:3], v[120:121], 0, s[8:9]
	global_load_dwordx4 v[30:33], v[2:3], off nt
	global_load_dwordx4 v[26:29], v[2:3], off offset:1024 nt
	global_load_dwordx4 v[22:25], v[2:3], off offset:2048 nt
	global_load_dwordx4 v[18:21], v[2:3], off offset:3072 nt
	s_add_i32 s8, s76, s70
	s_cmpk_lt_i32 s8, 0x4000
	s_cselect_b64 s[26:27], -1, 0
	s_and_b64 s[62:63], s[26:27], exec
	s_cselect_b32 s62, s8, s76
	s_ashr_i32 s63, s62, 31
	s_lshl_b64 s[62:63], s[62:63], 12
	v_lshl_add_u64 v[2:3], v[120:121], 0, s[62:63]
	global_load_dwordx4 v[14:17], v[2:3], off nt
	global_load_dwordx4 v[10:13], v[2:3], off offset:1024 nt
	s_waitcnt lgkmcnt(0)
	global_load_dwordx4 v[6:9], v[2:3], off offset:2048 nt
	s_nop 0
	global_load_dwordx4 v[2:5], v[2:3], off offset:3072 nt
	s_waitcnt vmcnt(7)
	v_mul_f32_e32 v131, v31, v31
	v_mul_f32_e32 v132, v33, v33
	s_waitcnt vmcnt(6)
	v_mul_f32_e32 v134, v27, v27
	v_mul_f32_e32 v136, v29, v29
	s_waitcnt vmcnt(5)
	v_mul_f32_e32 v138, v23, v23
	v_mul_f32_e32 v155, v25, v25
	v_fmac_f32_e32 v131, v30, v30
	v_fmac_f32_e32 v132, v32, v32
	v_fmac_f32_e32 v134, v26, v26
	v_fmac_f32_e32 v136, v28, v28
	s_waitcnt vmcnt(4)
	v_mul_f32_e32 v156, v19, v19
	v_mul_f32_e32 v157, v21, v21
	v_fmac_f32_e32 v138, v22, v22
	v_fmac_f32_e32 v155, v24, v24
	v_add_f32_e32 v131, v131, v132
	v_add_f32_e32 v132, v134, v136
	v_fmac_f32_e32 v156, v18, v18
	v_fmac_f32_e32 v157, v20, v20
	v_add_f32_e32 v134, v138, v155
	v_add_f32_e32 v131, v131, v132
	v_add_f32_e32 v131, v131, v134
	v_add_f32_e32 v132, v156, v157
	v_add_f32_e32 v131, v131, v132
	ds_bpermute_b32 v132, v34, v131
	s_waitcnt lgkmcnt(0)
	v_add_f32_e32 v131, v131, v132
	ds_bpermute_b32 v132, v105, v131
	s_waitcnt lgkmcnt(0)
	v_add_f32_e32 v131, v131, v132
	ds_bpermute_b32 v132, v124, v131
	s_waitcnt lgkmcnt(0)
	v_add_f32_e32 v131, v131, v132
	ds_bpermute_b32 v132, v126, v131
	s_waitcnt lgkmcnt(0)
	v_add_f32_e32 v131, v131, v132
	ds_bpermute_b32 v132, v128, v131
	s_waitcnt lgkmcnt(0)
	v_add_f32_e32 v131, v131, v132
	ds_bpermute_b32 v132, v130, v131
	s_and_saveexec_b64 s[78:79], s[4:5]
	s_cbranch_execz .LBB0_168
	s_lshl_b64 s[62:63], s[76:77], 2
	s_add_u32 s62, s83, s62
	s_waitcnt lgkmcnt(0)
	v_add_f32_e32 v131, v131, v132
	s_addc_u32 s63, s84, s63
	global_store_dword v35, v131, s[62:63]

; __device__ __forceinline__ unsigned pk2(float lo, float hi) { f32x2 v = {lo, hi}; bf2_t b = __builtin_convertvector(v, bf2_t); return __builtin_bit_cast(unsigned, b); }
; __device__ __forceinline__ void p0_prologue(const Args& a, LAS unsigned char* lds, int G, bool late_in_p1) {
;     ...
;       for (int m = gw; m < MEML; m += NGW) { const f32x4* xr = (const f32x4*)(mem + (size_t)m * D) + lane; f32x4 v[4]; float sq = 0.f;
; #pragma unroll
;           for (int j = 0; j < 4; ++j) { v[j] = xr[64 * j]; sq += (v[j][0] * v[j][0] + v[j][1] * v[j][1]) + (v[j][2] * v[j][2] + v[j][3] * v[j][3]); }
;           const float ri = 1.0f / sqrtf(wave_sum(sq) * (1.0f / D) + EPS);
;           u32x2* o8 = (u32x2*)(MN + (size_t)m * D) + lane;
; #pragma unroll
;           for (int j = 0; j < 4; ++j) { const f32x4 gg = *((const f32x4*)mg + lane + 64 * j); u32x2 w; w.x = pk2(v[j][0] * ri * gg[0], v[j][1] * ri * gg[1]); w.y = pk2(v[j][2] * ri * gg[2], v[j][3] * ri * gg[3]); o8[64 * j] = w; } } }
.LBB0_184:
	global_load_dwordx4 v[12:15], v[4:5], off offset:-3072 nt
	global_load_dwordx4 v[16:19], v[4:5], off offset:-2048 nt
	global_load_dwordx4 v[20:23], v[4:5], off offset:-1024 nt
	global_load_dwordx4 v[24:27], v[4:5], off nt
	global_load_dwordx4 v[28:31], v[122:123], off nt
	s_add_i32 s12, s12, s70
	v_lshl_add_u64 v[4:5], v[4:5], 0, s[14:15]
	s_cmpk_lt_i32 s12, 0x100
	s_waitcnt vmcnt(4)
	v_pk_mul_f32 v[32:33], v[14:15], v[14:15]
	v_pk_mul_f32 v[130:131], v[12:13], v[12:13]
	s_waitcnt vmcnt(3)
	v_pk_mul_f32 v[156:157], v[18:19], v[18:19]
	v_pk_mul_f32 v[158:159], v[16:17], v[16:17]
	v_pk_mov_b32 v[160:161], v[130:131], v[32:33] op_sel:[1,0]
	v_mov_b32_e32 v131, v33
	v_pk_mov_b32 v[32:33], v[158:159], v[156:157] op_sel:[1,0]
	v_mov_b32_e32 v159, v157
	s_waitcnt vmcnt(2)
	v_mul_f32_e32 v34, v21, v21
	v_mul_f32_e32 v124, v23, v23
	v_pk_add_f32 v[130:131], v[160:161], v[130:131]
	v_pk_add_f32 v[32:33], v[32:33], v[158:159]
	s_waitcnt vmcnt(1)
	v_mul_f32_e32 v105, v24, v24
	v_mul_f32_e32 v126, v25, v25
	v_mul_f32_e32 v128, v26, v26
	v_mul_f32_e32 v132, v27, v27
	v_pk_fma_f32 v[156:157], v[20:21], v[20:21], v[34:35] op_sel_hi:[1,1,0]
	v_pk_fma_f32 v[162:163], v[22:23], v[22:23], v[124:125] op_sel_hi:[1,1,0]
	v_pk_add_f32 v[130:131], v[130:131], v[130:131] op_sel:[0,1] op_sel_hi:[1,0]
	v_pk_add_f32 v[32:33], v[32:33], v[32:33] op_sel:[0,1] op_sel_hi:[1,0]
	v_mov_b32_e32 v157, v128
	v_mov_b32_e32 v163, v132
	v_mov_b32_e32 v131, v105
	v_mov_b32_e32 v33, v126
	v_pk_add_f32 v[156:157], v[156:157], v[162:163]
	v_pk_add_f32 v[32:33], v[130:131], v[32:33]
	s_nop 0
	v_pk_add_f32 v[32:33], v[32:33], v[156:157]
	s_nop 0
	v_add_f32_e32 v32, v32, v33
	ds_bpermute_b32 v33, v6, v32
	s_waitcnt lgkmcnt(0)
	v_add_f32_e32 v32, v32, v33
	ds_bpermute_b32 v33, v7, v32
	s_waitcnt lgkmcnt(0)
	v_add_f32_e32 v32, v32, v33
	ds_bpermute_b32 v33, v8, v32
	s_waitcnt lgkmcnt(0)
	v_add_f32_e32 v32, v32, v33
	ds_bpermute_b32 v33, v9, v32
	s_waitcnt lgkmcnt(0)
	v_add_f32_e32 v32, v32, v33
	ds_bpermute_b32 v33, v10, v32
	s_waitcnt lgkmcnt(0)
	v_add_f32_e32 v32, v32, v33
	ds_bpermute_b32 v33, v11, v32
	s_waitcnt lgkmcnt(0)
	v_add_f32_e32 v32, v32, v33
	v_fmamk_f32 v32, v32, 0x3a800000, v145
	v_mul_f32_e32 v33, 0x4f800000, v32
	v_cmp_gt_f32_e32 vcc, s90, v32
	s_nop 1
	v_cndmask_b32_e32 v32, v32, v33, vcc
	v_sqrt_f32_e32 v33, v32
	s_nop 0
	v_add_u32_e32 v34, -1, v33
	v_add_u32_e32 v105, 1, v33
	v_fma_f32 v124, -v34, v33, v32
	v_fma_f32 v126, -v105, v33, v32
	v_cmp_ge_f32_e64 s[8:9], 0, v124
	s_nop 1
	v_cndmask_b32_e64 v33, v33, v34, s[8:9]
	v_cmp_lt_f32_e64 s[8:9], 0, v126
	s_nop 1
	v_cndmask_b32_e64 v33, v33, v105, s[8:9]
	v_mul_f32_e32 v34, 0x37800000, v33
	v_cndmask_b32_e32 v33, v33, v34, vcc
	v_cmp_class_f32_e32 vcc, v32, v146
	s_nop 1
	v_cndmask_b32_e32 v32, v33, v32, vcc
	v_div_scale_f32 v33, s[8:9], v32, v32, 1.0
	v_rcp_f32_e32 v105, v33
	v_div_scale_f32 v34, vcc, 1.0, v32, 1.0
	v_fma_f32 v124, -v33, v105, 1.0
	v_fmac_f32_e32 v105, v124, v105
	v_mul_f32_e32 v124, v34, v105
	v_fma_f32 v126, -v33, v124, v34
	v_fmac_f32_e32 v124, v126, v105
	v_fma_f32 v33, -v33, v124, v34
	v_div_fmas_f32 v33, v33, v105, v124
	v_div_fixup_f32 v32, v33, v32, 1.0
	v_pk_mul_f32 v[12:13], v[12:13], v[32:33] op_sel_hi:[1,0]
	v_pk_mul_f32 v[14:15], v[14:15], v[32:33] op_sel_hi:[1,0]
	s_waitcnt vmcnt(0)
	v_pk_mul_f32 v[12:13], v[28:29], v[12:13]
	v_pk_mul_f32 v[14:15], v[30:31], v[14:15]
	v_cvt_pk_bf16_f32 v12, v12, v13
	v_cvt_pk_bf16_f32 v13, v14, v15
	global_store_dwordx2 v[2:3], v[12:13], off
	global_load_dwordx4 v[12:15], v[122:123], off offset:1024 nt
	v_pk_mul_f32 v[16:17], v[16:17], v[32:33] op_sel_hi:[1,0]
	v_pk_mul_f32 v[18:19], v[18:19], v[32:33] op_sel_hi:[1,0]
	s_waitcnt vmcnt(0)
	v_pk_mul_f32 v[12:13], v[12:13], v[16:17]
	v_pk_mul_f32 v[14:15], v[14:15], v[18:19]
	v_cvt_pk_bf16_f32 v12, v12, v13
	v_cvt_pk_bf16_f32 v13, v14, v15
	global_store_dwordx2 v[2:3], v[12:13], off offset:512
	global_load_dwordx4 v[12:15], v[122:123], off offset:2048 nt
	v_pk_mul_f32 v[16:17], v[20:21], v[32:33] op_sel_hi:[1,0]
	v_pk_mul_f32 v[18:19], v[22:23], v[32:33] op_sel_hi:[1,0]
	s_waitcnt vmcnt(0)
	v_pk_mul_f32 v[12:13], v[12:13], v[16:17]
	v_pk_mul_f32 v[14:15], v[14:15], v[18:19]
	v_cvt_pk_bf16_f32 v12, v12, v13
	v_cvt_pk_bf16_f32 v13, v14, v15
	global_store_dwordx2 v[2:3], v[12:13], off offset:1024
	global_load_dwordx4 v[12:15], v[122:123], off offset:3072 nt
	v_pk_mul_f32 v[16:17], v[24:25], v[32:33] op_sel_hi:[1,0]
	v_pk_mul_f32 v[18:19], v[26:27], v[32:33] op_sel_hi:[1,0]
	s_waitcnt vmcnt(0)
	v_pk_mul_f32 v[12:13], v[12:13], v[16:17]
	v_pk_mul_f32 v[14:15], v[14:15], v[18:19]
	v_cvt_pk_bf16_f32 v12, v12, v13
	v_cvt_pk_bf16_f32 v13, v14, v15
	global_store_dwordx2 v[2:3], v[12:13], off offset:1536
	v_lshl_add_u64 v[2:3], v[2:3], 0, s[46:47]
	s_cbranch_scc1 .LBB0_184
	s_branch .LBB0_10
